# GEMM K-loops P2/P5/P7: counted vmcnt keeps 2-slab prefetch in flight, LDS staging writes interleaved into MFMA stream, last iteration peeled
# speedup vs baseline: 1.0142x; 1.0142x over previous
; template <bool SWAP, class Epi>
; DI void gemm_tile(const u16* __restrict__ A, int lda, const u16* __restrict__ Bt, int ldb, int K, int m0, int n0, char* smem, Epi&& epi) {
;     ...
;       for (int i = 0; i < 16; ++i) acc[a][b][i] = 0.f;
;   const int srow = tid >> 3, skc = tid & 7;
;   const u16* ag = A + (size_t)(m0 + srow) * lda + skc * 8;
;   const u16* bg = Bt + (size_t)(n0 + srow) * ldb + skc * 8;
;   u16* asw = As + srow * 72 + skc * 8;
;   u16* bsw = Bs + srow * 72 + skc * 8;
;   u32x4 ra0[4], rb0[4], ra1[4], rb1[4];
; #pragma unroll
;   for (int i = 0; i < 4; ++i) { ra0[i] = *(const u32x4*)(ag + (size_t)i * 32 * lda); rb0[i] = *(const u32x4*)(bg + (size_t)i * 32 * ldb); }
; #pragma unroll
;   for (int i = 0; i < 4; ++i) { ra1[i] = *(const u32x4*)(ag + (size_t)i * 32 * lda + 64); rb1[i] = *(const u32x4*)(bg + (size_t)i * 32 * ldb + 64); }
;   __syncthreads();
; #pragma unroll
;   for (int i = 0; i < 4; ++i) { *(u32x4*)(asw + 32 * i * 72) = ra0[i]; *(u32x4*)(bsw + 32 * i * 72) = rb0[i]; }
;   __syncthreads();
;   const int KT = K >> 6;
;   const u16* Asb = As + (wm * 64 + r) * 72 + hi * 8;
;   const u16* Bsb = Bs + (wn * 64 + r) * 72 + hi * 8;
;   auto compute = [&](int buf) __attribute__((always_inline)) {
;     bf16x8 af[2][2], bfr[2][2];
;     af[0][0] = *(const bf16x8*)(Asb + buf * 128 * 72);
;     af[0][1] = *(const bf16x8*)(Asb + buf * 128 * 72 + 32 * 72);
;     bfr[0][0] = *(const bf16x8*)(Bsb + buf * 128 * 72);
;     bfr[0][1] = *(const bf16x8*)(Bsb + buf * 128 * 72 + 32 * 72);
; #pragma unroll
;     for (int ks = 0; ks < 4; ++ks) {
;       const int c = ks & 1, n = c ^ 1;
;       if (ks < 3) {
;         af[n][0] = *(const bf16x8*)(Asb + buf * 128 * 72 + (ks + 1) * 16);
;         af[n][1] = *(const bf16x8*)(Asb + buf * 128 * 72 + 32 * 72 + (ks + 1) * 16);
;         bfr[n][0] = *(const bf16x8*)(Bsb + buf * 128 * 72 + (ks + 1) * 16);
;         bfr[n][1] = *(const bf16x8*)(Bsb + buf * 128 * 72 + 32 * 72 + (ks + 1) * 16);
;       }
;       __builtin_amdgcn_sched_barrier(0);
; #pragma unroll
;       for (int mi = 0; mi < 2; ++mi)
; #pragma unroll
;         for (int ni = 0; ni < 2; ++ni) {
;           if (SWAP) acc[mi][ni] = MFMA(bfr[c][ni], af[c][mi], acc[mi][ni]);
;           else acc[mi][ni] = MFMA(af[c][mi], bfr[c][ni], acc[mi][ni]);
;         }
;       __builtin_amdgcn_sched_barrier(0);
;     }
;   };
;   for (int kt = 0; kt < KT; kt += 2) {
.LBB0_385:
	s_ashr_i32 s10, s21, 31
	s_lshr_b32 s10, s10, 26
	s_add_i32 s10, s21, s10
	s_and_b32 s11, s10, 0x1ffffc0
	s_sub_i32 s11, s21, s11
	s_lshl_b32 s22, s11, 7
	s_lshl_b32 s10, s10, 1
	s_waitcnt lgkmcnt(0)
	v_or_b32_e32 v2, s22, v1
	s_and_b32 s23, s10, 0xffffff80
	v_ashrrev_i32_e32 v3, 31, v2
	v_lshlrev_b64 v[22:23], 12, v[2:3]
	v_or_b32_e32 v2, s23, v1
	v_lshl_add_u64 v[4:5], v[132:133], 0, v[22:23]
	v_ashrrev_i32_e32 v3, 31, v2
	v_lshlrev_b64 v[24:25], 12, v[2:3]
	v_add_co_u32_e32 v8, vcc, s16, v4
	v_lshl_add_u64 v[6:7], v[134:135], 0, v[24:25]
	s_nop 0
	v_addc_co_u32_e32 v9, vcc, 0, v5, vcc
	v_add_co_u32_e32 v10, vcc, s16, v6
	global_load_dwordx4 v[66:69], v[4:5], off
	global_load_dwordx4 v[70:73], v[6:7], off
	v_addc_co_u32_e32 v11, vcc, 0, v7, vcc
	v_add_co_u32_e32 v12, vcc, s17, v4
	global_load_dwordx4 v[74:77], v[8:9], off
	global_load_dwordx4 v[78:81], v[10:11], off
	v_addc_co_u32_e32 v13, vcc, 0, v5, vcc
	v_add_co_u32_e32 v14, vcc, s17, v6
	global_load_dwordx4 v[82:85], v[12:13], off
	s_nop 0
	v_addc_co_u32_e32 v15, vcc, 0, v7, vcc
	v_add_co_u32_e32 v16, vcc, s18, v6
	global_load_dwordx4 v[86:89], v[14:15], off
	s_nop 0
	v_addc_co_u32_e32 v17, vcc, 0, v7, vcc
	v_add_co_u32_e32 v18, vcc, s18, v4
	global_load_dwordx4 v[94:97], v[16:17], off
	s_nop 0
	v_addc_co_u32_e32 v19, vcc, 0, v5, vcc
	global_load_dwordx4 v[90:93], v[18:19], off
	global_load_dwordx4 v[98:101], v[4:5], off offset:128
	global_load_dwordx4 v[102:105], v[6:7], off offset:128
	global_load_dwordx4 v[106:109], v[8:9], off offset:128
	global_load_dwordx4 v[110:113], v[10:11], off offset:128
	global_load_dwordx4 v[114:117], v[12:13], off offset:128
	global_load_dwordx4 v[118:121], v[14:15], off offset:128
	global_load_dwordx4 v[122:125], v[18:19], off offset:128
	global_load_dwordx4 v[126:129], v[16:17], off offset:128
	s_mov_b32 s24, 0
	v_mov_b32_e32 v2, 0
	v_mov_b32_e32 v3, v131
	v_mov_b32_e32 v4, v131
	v_mov_b32_e32 v5, v131
	v_mov_b32_e32 v6, v131
	v_mov_b32_e32 v7, v131
	v_mov_b32_e32 v8, v131
	v_mov_b32_e32 v9, v131
	v_mov_b32_e32 v10, v131
	v_mov_b32_e32 v11, v131
	v_mov_b32_e32 v12, v131
	v_mov_b32_e32 v13, v131
	v_mov_b32_e32 v14, v131
	v_mov_b32_e32 v15, v131
	v_mov_b32_e32 v16, v131
	v_mov_b32_e32 v17, v131
	v_mov_b32_e32 v18, 0
	v_mov_b32_e32 v19, v131
	v_mov_b32_e32 v20, v131
	v_lshl_add_u64 v[138:139], s[82:83], 0, v[24:25]
	v_lshl_add_u64 v[140:141], s[82:83], 0, v[22:23]
	v_mov_b32_e32 v21, v131
	v_mov_b32_e32 v22, v131
	v_mov_b32_e32 v23, v131
	v_mov_b32_e32 v24, v131
	v_mov_b32_e32 v25, v131
	v_mov_b32_e32 v26, v131
	v_mov_b32_e32 v27, v131
	v_mov_b32_e32 v28, v131
	v_mov_b32_e32 v29, v131
	v_mov_b32_e32 v30, v131
	v_mov_b32_e32 v31, v131
	v_mov_b32_e32 v32, v131
	v_mov_b32_e32 v33, v131
	v_mov_b32_e32 v34, 0
	v_mov_b32_e32 v35, v131
	v_mov_b32_e32 v36, v131
	v_mov_b32_e32 v37, v131
	v_mov_b32_e32 v38, v131
	v_mov_b32_e32 v39, v131
	v_mov_b32_e32 v40, v131
	v_mov_b32_e32 v41, v131
	v_mov_b32_e32 v42, v131
	v_mov_b32_e32 v43, v131
	v_mov_b32_e32 v44, v131
	v_mov_b32_e32 v45, v131
	v_mov_b32_e32 v46, v131
	v_mov_b32_e32 v47, v131
	v_mov_b32_e32 v48, v131
	v_mov_b32_e32 v49, v131
	v_mov_b32_e32 v50, 0
	v_mov_b32_e32 v51, v131
	v_mov_b32_e32 v52, v131
	v_mov_b32_e32 v53, v131
	v_mov_b32_e32 v54, v131
	v_mov_b32_e32 v55, v131
	v_mov_b32_e32 v56, v131
	v_mov_b32_e32 v57, v131
	v_mov_b32_e32 v58, v131
	v_mov_b32_e32 v59, v131
	v_mov_b32_e32 v60, v131
	v_mov_b32_e32 v61, v131
	v_mov_b32_e32 v62, v131
	v_mov_b32_e32 v63, v131
	v_mov_b32_e32 v64, v131
	v_mov_b32_e32 v65, v131
	s_waitcnt lgkmcnt(0)
	s_barrier
	s_waitcnt vmcnt(14)
	ds_write_b128 v146, v[70:73] offset:36880
	ds_write_b128 v146, v[66:69] offset:16
	s_waitcnt vmcnt(12)
	ds_write_b128 v146, v[78:81] offset:41488
	s_waitcnt vmcnt(10)
	ds_write_b128 v146, v[86:89] offset:46096
	s_waitcnt vmcnt(9)
	ds_write_b128 v146, v[94:97] offset:50704
	ds_write_b128 v146, v[74:77] offset:4624
	ds_write_b128 v146, v[82:85] offset:9232
	s_waitcnt vmcnt(8)
	ds_write_b128 v146, v[90:93] offset:13840
	s_waitcnt lgkmcnt(0)
	s_barrier
	s_branch .LBB0_387
.LBB0_387:
	v_lshl_add_u64 v[144:145], v[140:141], 0, v[136:137]
	v_lshl_add_u64 v[142:143], v[138:139], 0, v[136:137]
	v_add_co_u32_e32 v66, vcc, 0x6538000, v144
	s_nop 1
	v_addc_co_u32_e32 v67, vcc, 0, v145, vcc
	v_add_co_u32_e32 v70, vcc, 0xb8000, v142
	global_load_dwordx4 v[66:69], v[66:67], off offset:256
	s_nop 0
	v_addc_co_u32_e32 v71, vcc, 0, v143, vcc
	v_add_co_u32_e32 v74, vcc, 0x6558000, v144
	global_load_dwordx4 v[70:73], v[70:71], off offset:256
	s_nop 0
	v_addc_co_u32_e32 v75, vcc, 0, v145, vcc
	v_add_co_u32_e32 v78, vcc, 0xd8000, v142
	global_load_dwordx4 v[74:77], v[74:75], off offset:256
	s_nop 0
	v_addc_co_u32_e32 v79, vcc, 0, v143, vcc
	v_add_co_u32_e32 v82, vcc, 0x6578000, v144
	global_load_dwordx4 v[78:81], v[78:79], off offset:256
	s_nop 0
	v_addc_co_u32_e32 v83, vcc, 0, v145, vcc
	v_add_co_u32_e32 v86, vcc, 0xf8000, v142
	global_load_dwordx4 v[82:85], v[82:83], off offset:256
	s_nop 0
	v_addc_co_u32_e32 v87, vcc, 0, v143, vcc
	v_add_co_u32_e32 v90, vcc, 0x6598000, v144
	global_load_dwordx4 v[86:89], v[86:87], off offset:256
	s_nop 0
	v_addc_co_u32_e32 v91, vcc, 0, v145, vcc
	v_add_co_u32_e32 v94, vcc, 0x118000, v142
	global_load_dwordx4 v[90:93], v[90:91], off offset:256
	s_nop 0
	v_addc_co_u32_e32 v95, vcc, 0, v143, vcc
	global_load_dwordx4 v[94:97], v[94:95], off offset:256
	ds_read_b128 v[154:157], v149 offset:16
	ds_read_b128 v[158:161], v149 offset:48
	ds_read_b128 v[162:165], v149 offset:4624
	ds_read_b128 v[166:169], v149 offset:4656
	ds_read_b128 v[170:173], v150 offset:36880
	ds_read_b128 v[174:177], v150 offset:36912
	ds_read_b128 v[178:181], v150 offset:41488
	ds_read_b128 v[182:185], v150 offset:41520
	s_waitcnt lgkmcnt(3)
; #define MFMA(a, b, c) __builtin_amdgcn_mfma_f32_32x32x16_bf16((a), (b), (c), 0, 0, 0)
; template <bool SWAP, class Epi>
; DI void gemm_tile(const u16* __restrict__ A, int lda, const u16* __restrict__ Bt, int ldb, int K, int m0, int n0, char* smem, Epi&& epi) {
;     ...
;   auto compute = [&](int buf) __attribute__((always_inline)) {
;     bf16x8 af[2][2], bfr[2][2];
;     af[0][0] = *(const bf16x8*)(Asb + buf * 128 * 72);
;     af[0][1] = *(const bf16x8*)(Asb + buf * 128 * 72 + 32 * 72);
;     bfr[0][0] = *(const bf16x8*)(Bsb + buf * 128 * 72);
;     bfr[0][1] = *(const bf16x8*)(Bsb + buf * 128 * 72 + 32 * 72);
; #pragma unroll
;     for (int ks = 0; ks < 4; ++ks) {
;       const int c = ks & 1, n = c ^ 1;
;       if (ks < 3) {
;         af[n][0] = *(const bf16x8*)(Asb + buf * 128 * 72 + (ks + 1) * 16);
;         af[n][1] = *(const bf16x8*)(Asb + buf * 128 * 72 + 32 * 72 + (ks + 1) * 16);
;         bfr[n][0] = *(const bf16x8*)(Bsb + buf * 128 * 72 + (ks + 1) * 16);
;         bfr[n][1] = *(const bf16x8*)(Bsb + buf * 128 * 72 + 32 * 72 + (ks + 1) * 16);
;       }
;       __builtin_amdgcn_sched_barrier(0);
; #pragma unroll
;       for (int mi = 0; mi < 2; ++mi)
; #pragma unroll
;         for (int ni = 0; ni < 2; ++ni) {
;           if (SWAP) acc[mi][ni] = MFMA(bfr[c][ni], af[c][mi], acc[mi][ni]);
;           else acc[mi][ni] = MFMA(af[c][mi], bfr[c][ni], acc[mi][ni]);
;         }
;       __builtin_amdgcn_sched_barrier(0);
;     }
;   };
;   for (int kt = 0; kt < KT; kt += 2) {
;     if (kt + 2 < KT) {
;       const int k0 = (kt + 2) << 6;
; #pragma unroll
;       for (int i = 0; i < 4; ++i) { ra0[i] = *(const u32x4*)(ag + (size_t)i * 32 * lda + k0); rb0[i] = *(const u32x4*)(bg + (size_t)i * 32 * ldb + k0); }
;     }
;     compute(0);
; #pragma unroll
;     for (int i = 0; i < 4; ++i) { *(u32x4*)(asw + 128 * 72 + 32 * i * 72) = ra1[i]; *(u32x4*)(bsw + 128 * 72 + 32 * i * 72) = rb1[i]; }
;     __syncthreads();
;     if (kt + 3 < KT) {
;       const int k0 = (kt + 3) << 6;
; #pragma unroll
;       for (int i = 0; i < 4; ++i) { ra1[i] = *(const u32x4*)(ag + (size_t)i * 32 * lda + k0); rb1[i] = *(const u32x4*)(bg + (size_t)i * 32 * ldb + k0); }
;     }
;     compute(1);
;     if (kt + 2 < KT) {
; #pragma unroll
;       for (int i = 0; i < 4; ++i) { *(u32x4*)(asw + 32 * i * 72) = ra0[i]; *(u32x4*)(bsw + 32 * i * 72) = rb0[i]; }
;     }
;     __syncthreads();
	v_mfma_f32_32x32x16_bf16 v[50:65], v[170:173], v[154:157], v[50:65]
	s_waitcnt lgkmcnt(1)
	v_mfma_f32_32x32x16_bf16 v[34:49], v[178:181], v[154:157], v[34:49]
	v_mfma_f32_32x32x16_bf16 v[18:33], v[170:173], v[162:165], v[18:33]
	v_mfma_f32_32x32x16_bf16 v[2:17], v[178:181], v[162:165], v[2:17]
	ds_read_b128 v[154:157], v149 offset:80
	ds_read_b128 v[162:165], v149 offset:4688
	ds_read_b128 v[170:173], v150 offset:36944
	ds_read_b128 v[178:181], v150 offset:41552
	v_mfma_f32_32x32x16_bf16 v[50:65], v[174:177], v[158:161], v[50:65]
	s_waitcnt lgkmcnt(4)
	v_mfma_f32_32x32x16_bf16 v[34:49], v[182:185], v[158:161], v[34:49]
	v_mfma_f32_32x32x16_bf16 v[18:33], v[174:177], v[166:169], v[18:33]
	v_mfma_f32_32x32x16_bf16 v[2:17], v[182:185], v[166:169], v[2:17]
	ds_read_b128 v[158:161], v149 offset:112
	ds_read_b128 v[166:169], v149 offset:4720
	ds_read_b128 v[174:177], v150 offset:36976
	ds_read_b128 v[182:185], v150 offset:41584
	s_waitcnt lgkmcnt(5)
	v_mfma_f32_32x32x16_bf16 v[50:65], v[170:173], v[154:157], v[50:65]
	s_waitcnt vmcnt(14)
	ds_write_b128 v146, v[98:101] offset:18448
	ds_write_b128 v146, v[102:105] offset:55312
	s_waitcnt lgkmcnt(6)
	v_mfma_f32_32x32x16_bf16 v[34:49], v[178:181], v[154:157], v[34:49]
	v_mfma_f32_32x32x16_bf16 v[18:33], v[170:173], v[162:165], v[18:33]
	s_waitcnt vmcnt(12)
	ds_write_b128 v146, v[106:109] offset:23056
	ds_write_b128 v146, v[110:113] offset:59920
	v_mfma_f32_32x32x16_bf16 v[2:17], v[178:181], v[162:165], v[2:17]
	s_waitcnt vmcnt(10)
	ds_write_b128 v146, v[114:117] offset:27664
	ds_write_b128 v146, v[118:121] offset:64528
	s_waitcnt lgkmcnt(7)
	v_mfma_f32_32x32x16_bf16 v[50:65], v[174:177], v[158:161], v[50:65]
	s_waitcnt vmcnt(8)
	ds_write_b128 v146, v[122:125] offset:32272
	ds_write_b128 v147, v[126:129] offset:32256
	s_waitcnt lgkmcnt(8)
	v_mfma_f32_32x32x16_bf16 v[34:49], v[182:185], v[158:161], v[34:49]
	v_mfma_f32_32x32x16_bf16 v[18:33], v[174:177], v[166:169], v[18:33]
	v_mfma_f32_32x32x16_bf16 v[2:17], v[182:185], v[166:169], v[2:17]
	s_waitcnt lgkmcnt(0)
	s_barrier
	v_add_co_u32_e32 v98, vcc, 0x6538000, v144
	s_nop 1
	v_addc_co_u32_e32 v99, vcc, 0, v145, vcc
	v_add_co_u32_e32 v102, vcc, 0xb8000, v142
	global_load_dwordx4 v[98:101], v[98:99], off offset:384
	s_nop 0
	v_addc_co_u32_e32 v103, vcc, 0, v143, vcc
	v_add_co_u32_e32 v106, vcc, 0x6558000, v144
	global_load_dwordx4 v[102:105], v[102:103], off offset:384
	s_nop 0
	v_addc_co_u32_e32 v107, vcc, 0, v145, vcc
	v_add_co_u32_e32 v110, vcc, 0xd8000, v142
	global_load_dwordx4 v[106:109], v[106:107], off offset:384
	s_nop 0
	v_addc_co_u32_e32 v111, vcc, 0, v143, vcc
	v_add_co_u32_e32 v114, vcc, 0x6578000, v144
	global_load_dwordx4 v[110:113], v[110:111], off offset:384
	s_nop 0
	v_addc_co_u32_e32 v115, vcc, 0, v145, vcc
	v_add_co_u32_e32 v118, vcc, 0xf8000, v142
	global_load_dwordx4 v[114:117], v[114:115], off offset:384
	s_nop 0
	v_addc_co_u32_e32 v119, vcc, 0, v143, vcc
	v_add_co_u32_e32 v122, vcc, 0x6598000, v144
	global_load_dwordx4 v[118:121], v[118:119], off offset:384
	s_nop 0
	v_addc_co_u32_e32 v123, vcc, 0, v145, vcc
	v_add_co_u32_e32 v126, vcc, 0x118000, v142
	global_load_dwordx4 v[122:125], v[122:123], off offset:384
	s_nop 0
	v_addc_co_u32_e32 v127, vcc, 0, v143, vcc
	global_load_dwordx4 v[126:129], v[126:127], off offset:384
	ds_read_b128 v[142:145], v149 offset:18448
	ds_read_b128 v[154:157], v149 offset:18480
	ds_read_b128 v[158:161], v149 offset:23056
	ds_read_b128 v[162:165], v149 offset:23088
	ds_read_b128 v[166:169], v150 offset:55312
	ds_read_b128 v[170:173], v150 offset:55344
	ds_read_b128 v[174:177], v150 offset:59920
	ds_read_b128 v[178:181], v150 offset:59952
	s_waitcnt lgkmcnt(3)
	v_mfma_f32_32x32x16_bf16 v[50:65], v[166:169], v[142:145], v[50:65]
	s_waitcnt lgkmcnt(1)
	v_mfma_f32_32x32x16_bf16 v[34:49], v[174:177], v[142:145], v[34:49]
	v_mfma_f32_32x32x16_bf16 v[18:33], v[166:169], v[158:161], v[18:33]
	v_mfma_f32_32x32x16_bf16 v[2:17], v[174:177], v[158:161], v[2:17]
	ds_read_b128 v[142:145], v149 offset:18512
	ds_read_b128 v[158:161], v149 offset:23120
	ds_read_b128 v[166:169], v150 offset:55376
	ds_read_b128 v[174:177], v150 offset:59984
	v_mfma_f32_32x32x16_bf16 v[50:65], v[170:173], v[154:157], v[50:65]
	s_waitcnt lgkmcnt(4)
	v_mfma_f32_32x32x16_bf16 v[34:49], v[178:181], v[154:157], v[34:49]
	v_mfma_f32_32x32x16_bf16 v[18:33], v[170:173], v[162:165], v[18:33]
	v_mfma_f32_32x32x16_bf16 v[2:17], v[178:181], v[162:165], v[2:17]
	ds_read_b128 v[154:157], v149 offset:18544
	ds_read_b128 v[162:165], v149 offset:23152
	ds_read_b128 v[170:173], v150 offset:55408
	ds_read_b128 v[178:181], v150 offset:60016
	s_waitcnt lgkmcnt(5)
	v_mfma_f32_32x32x16_bf16 v[50:65], v[166:169], v[142:145], v[50:65]
	s_waitcnt vmcnt(14)
	ds_write_b128 v146, v[66:69] offset:16
	ds_write_b128 v146, v[70:73] offset:36880
	s_waitcnt lgkmcnt(6)
	v_mfma_f32_32x32x16_bf16 v[34:49], v[174:177], v[142:145], v[34:49]
	v_mfma_f32_32x32x16_bf16 v[18:33], v[166:169], v[158:161], v[18:33]
	s_waitcnt vmcnt(12)
	ds_write_b128 v146, v[74:77] offset:4624
	ds_write_b128 v146, v[78:81] offset:41488
	v_mfma_f32_32x32x16_bf16 v[2:17], v[174:177], v[158:161], v[2:17]
	s_waitcnt vmcnt(10)
	ds_write_b128 v146, v[82:85] offset:9232
	ds_write_b128 v146, v[86:89] offset:46096
	s_waitcnt lgkmcnt(7)
	v_mfma_f32_32x32x16_bf16 v[50:65], v[170:173], v[154:157], v[50:65]
	s_waitcnt vmcnt(8)
	ds_write_b128 v146, v[90:93] offset:13840
	ds_write_b128 v146, v[94:97] offset:50704
	s_waitcnt lgkmcnt(8)
	v_mfma_f32_32x32x16_bf16 v[34:49], v[178:181], v[154:157], v[34:49]
	v_mfma_f32_32x32x16_bf16 v[18:33], v[170:173], v[162:165], v[18:33]
	v_mfma_f32_32x32x16_bf16 v[2:17], v[178:181], v[162:165], v[2:17]
	s_add_i32 s24, s24, 2
	v_lshl_add_u64 v[138:139], v[138:139], 0, s[8:9]
	v_lshl_add_u64 v[140:141], v[140:141], 0, s[8:9]
	s_waitcnt lgkmcnt(0)
	s_barrier
; #define MFMA(a, b, c) __builtin_amdgcn_mfma_f32_32x32x16_bf16((a), (b), (c), 0, 0, 0)
; template <bool SWAP, class Epi>
; DI void gemm_tile(const u16* __restrict__ A, int lda, const u16* __restrict__ Bt, int ldb, int K, int m0, int n0, char* smem, Epi&& epi) {
;     ...
;   auto compute = [&](int buf) __attribute__((always_inline)) {
;     bf16x8 af[2][2], bfr[2][2];
;     af[0][0] = *(const bf16x8*)(Asb + buf * 128 * 72);
;     af[0][1] = *(const bf16x8*)(Asb + buf * 128 * 72 + 32 * 72);
;     bfr[0][0] = *(const bf16x8*)(Bsb + buf * 128 * 72);
;     bfr[0][1] = *(const bf16x8*)(Bsb + buf * 128 * 72 + 32 * 72);
; #pragma unroll
;     for (int ks = 0; ks < 4; ++ks) {
;       const int c = ks & 1, n = c ^ 1;
;       if (ks < 3) {
;         af[n][0] = *(const bf16x8*)(Asb + buf * 128 * 72 + (ks + 1) * 16);
;         af[n][1] = *(const bf16x8*)(Asb + buf * 128 * 72 + 32 * 72 + (ks + 1) * 16);
;         bfr[n][0] = *(const bf16x8*)(Bsb + buf * 128 * 72 + (ks + 1) * 16);
;         bfr[n][1] = *(const bf16x8*)(Bsb + buf * 128 * 72 + 32 * 72 + (ks + 1) * 16);
;       }
;       __builtin_amdgcn_sched_barrier(0);
; #pragma unroll
;       for (int mi = 0; mi < 2; ++mi)
; #pragma unroll
;         for (int ni = 0; ni < 2; ++ni) {
;           if (SWAP) acc[mi][ni] = MFMA(bfr[c][ni], af[c][mi], acc[mi][ni]);
;           else acc[mi][ni] = MFMA(af[c][mi], bfr[c][ni], acc[mi][ni]);
;         }
;       __builtin_amdgcn_sched_barrier(0);
;     }
;   };
;   for (int kt = 0; kt < KT; kt += 2) {
;     if (kt + 2 < KT) {
;       const int k0 = (kt + 2) << 6;
; #pragma unroll
;       for (int i = 0; i < 4; ++i) { ra0[i] = *(const u32x4*)(ag + (size_t)i * 32 * lda + k0); rb0[i] = *(const u32x4*)(bg + (size_t)i * 32 * ldb + k0); }
;     }
;     compute(0);
; #pragma unroll
;     for (int i = 0; i < 4; ++i) { *(u32x4*)(asw + 128 * 72 + 32 * i * 72) = ra1[i]; *(u32x4*)(bsw + 128 * 72 + 32 * i * 72) = rb1[i]; }
;     __syncthreads();
;     if (kt + 3 < KT) {
;       const int k0 = (kt + 3) << 6;
; #pragma unroll
;       for (int i = 0; i < 4; ++i) { ra1[i] = *(const u32x4*)(ag + (size_t)i * 32 * lda + k0); rb1[i] = *(const u32x4*)(bg + (size_t)i * 32 * ldb + k0); }
;     }
;     compute(1);
;     if (kt + 2 < KT) {
; #pragma unroll
;       for (int i = 0; i < 4; ++i) { *(u32x4*)(asw + 32 * i * 72) = ra0[i]; *(u32x4*)(bsw + 32 * i * 72) = rb0[i]; }
;     }
;     __syncthreads();
	s_cmp_lt_u32 s24, 30
	s_cbranch_scc1 .LBB0_387
	ds_read_b128 v[154:157], v149 offset:16
	ds_read_b128 v[158:161], v149 offset:48
	ds_read_b128 v[162:165], v149 offset:4624
	ds_read_b128 v[166:169], v149 offset:4656
	ds_read_b128 v[170:173], v150 offset:36880
	ds_read_b128 v[174:177], v150 offset:36912
	ds_read_b128 v[178:181], v150 offset:41488
	ds_read_b128 v[182:185], v150 offset:41520
	s_waitcnt lgkmcnt(3)
	v_mfma_f32_32x32x16_bf16 v[50:65], v[170:173], v[154:157], v[50:65]
	s_waitcnt lgkmcnt(1)
	v_mfma_f32_32x32x16_bf16 v[34:49], v[178:181], v[154:157], v[34:49]
	v_mfma_f32_32x32x16_bf16 v[18:33], v[170:173], v[162:165], v[18:33]
	v_mfma_f32_32x32x16_bf16 v[2:17], v[178:181], v[162:165], v[2:17]
	ds_read_b128 v[154:157], v149 offset:80
	ds_read_b128 v[162:165], v149 offset:4688
	ds_read_b128 v[170:173], v150 offset:36944
	ds_read_b128 v[178:181], v150 offset:41552
	v_mfma_f32_32x32x16_bf16 v[50:65], v[174:177], v[158:161], v[50:65]
	s_waitcnt lgkmcnt(4)
	v_mfma_f32_32x32x16_bf16 v[34:49], v[182:185], v[158:161], v[34:49]
	v_mfma_f32_32x32x16_bf16 v[18:33], v[174:177], v[166:169], v[18:33]
	v_mfma_f32_32x32x16_bf16 v[2:17], v[182:185], v[166:169], v[2:17]
	ds_read_b128 v[158:161], v149 offset:112
	ds_read_b128 v[166:169], v149 offset:4720
	ds_read_b128 v[174:177], v150 offset:36976
	ds_read_b128 v[182:185], v150 offset:41584
	s_waitcnt lgkmcnt(5)
	v_mfma_f32_32x32x16_bf16 v[50:65], v[170:173], v[154:157], v[50:65]
	s_waitcnt vmcnt(6)
	ds_write_b128 v146, v[98:101] offset:18448
	ds_write_b128 v146, v[102:105] offset:55312
	s_waitcnt lgkmcnt(6)
	v_mfma_f32_32x32x16_bf16 v[34:49], v[178:181], v[154:157], v[34:49]
	v_mfma_f32_32x32x16_bf16 v[18:33], v[170:173], v[162:165], v[18:33]
	s_waitcnt vmcnt(4)
	ds_write_b128 v146, v[106:109] offset:23056
	ds_write_b128 v146, v[110:113] offset:59920
	v_mfma_f32_32x32x16_bf16 v[2:17], v[178:181], v[162:165], v[2:17]
	s_waitcnt vmcnt(2)
	ds_write_b128 v146, v[114:117] offset:27664
	ds_write_b128 v146, v[118:121] offset:64528
	s_waitcnt lgkmcnt(7)
	v_mfma_f32_32x32x16_bf16 v[50:65], v[174:177], v[158:161], v[50:65]
	s_waitcnt vmcnt(0)
	ds_write_b128 v146, v[122:125] offset:32272
	ds_write_b128 v147, v[126:129] offset:32256
	s_waitcnt lgkmcnt(8)
	v_mfma_f32_32x32x16_bf16 v[34:49], v[182:185], v[158:161], v[34:49]
	v_mfma_f32_32x32x16_bf16 v[18:33], v[174:177], v[166:169], v[18:33]
	v_mfma_f32_32x32x16_bf16 v[2:17], v[182:185], v[166:169], v[2:17]
	s_waitcnt lgkmcnt(0)
	s_barrier
	ds_read_b128 v[142:145], v149 offset:18448
	ds_read_b128 v[154:157], v149 offset:18480
	ds_read_b128 v[158:161], v149 offset:23056
	ds_read_b128 v[162:165], v149 offset:23088
	ds_read_b128 v[166:169], v150 offset:55312
	ds_read_b128 v[170:173], v150 offset:55344
	ds_read_b128 v[174:177], v150 offset:59920
	ds_read_b128 v[178:181], v150 offset:59952
	s_waitcnt lgkmcnt(3)
	v_mfma_f32_32x32x16_bf16 v[50:65], v[166:169], v[142:145], v[50:65]
	s_waitcnt lgkmcnt(1)
	v_mfma_f32_32x32x16_bf16 v[34:49], v[174:177], v[142:145], v[34:49]
	v_mfma_f32_32x32x16_bf16 v[18:33], v[166:169], v[158:161], v[18:33]
	v_mfma_f32_32x32x16_bf16 v[2:17], v[174:177], v[158:161], v[2:17]
	ds_read_b128 v[142:145], v149 offset:18512
	ds_read_b128 v[158:161], v149 offset:23120
	ds_read_b128 v[166:169], v150 offset:55376
	ds_read_b128 v[174:177], v150 offset:59984
	v_mfma_f32_32x32x16_bf16 v[50:65], v[170:173], v[154:157], v[50:65]
	s_waitcnt lgkmcnt(4)
	v_mfma_f32_32x32x16_bf16 v[34:49], v[178:181], v[154:157], v[34:49]
	v_mfma_f32_32x32x16_bf16 v[18:33], v[170:173], v[162:165], v[18:33]
	v_mfma_f32_32x32x16_bf16 v[2:17], v[178:181], v[162:165], v[2:17]
	ds_read_b128 v[154:157], v149 offset:18544
	ds_read_b128 v[162:165], v149 offset:23152
	ds_read_b128 v[170:173], v150 offset:55408
	ds_read_b128 v[178:181], v150 offset:60016
	s_waitcnt lgkmcnt(5)
	v_mfma_f32_32x32x16_bf16 v[50:65], v[166:169], v[142:145], v[50:65]
	s_waitcnt lgkmcnt(4)
	v_mfma_f32_32x32x16_bf16 v[34:49], v[174:177], v[142:145], v[34:49]
	v_mfma_f32_32x32x16_bf16 v[18:33], v[166:169], v[158:161], v[18:33]
	v_mfma_f32_32x32x16_bf16 v[2:17], v[174:177], v[158:161], v[2:17]
	s_waitcnt lgkmcnt(1)
	v_mfma_f32_32x32x16_bf16 v[50:65], v[170:173], v[154:157], v[50:65]
	s_waitcnt lgkmcnt(0)
	v_mfma_f32_32x32x16_bf16 v[34:49], v[178:181], v[154:157], v[34:49]
	v_mfma_f32_32x32x16_bf16 v[18:33], v[170:173], v[162:165], v[18:33]
	v_mfma_f32_32x32x16_bf16 v[2:17], v[178:181], v[162:165], v[2:17]
	s_waitcnt lgkmcnt(0)
	s_barrier
	s_branch .LBB0_393

; template <bool SWAP, class Epi>
; DI void gemm_tile(const u16* __restrict__ A, int lda, const u16* __restrict__ Bt, int ldb, int K, int m0, int n0, char* smem, Epi&& epi) {
;     ...
;       for (int i = 0; i < 16; ++i) acc[a][b][i] = 0.f;
;   const int srow = tid >> 3, skc = tid & 7;
;   const u16* ag = A + (size_t)(m0 + srow) * lda + skc * 8;
;   const u16* bg = Bt + (size_t)(n0 + srow) * ldb + skc * 8;
;   u16* asw = As + srow * 72 + skc * 8;
;   u16* bsw = Bs + srow * 72 + skc * 8;
;   u32x4 ra0[4], rb0[4], ra1[4], rb1[4];
; #pragma unroll
;   for (int i = 0; i < 4; ++i) { ra0[i] = *(const u32x4*)(ag + (size_t)i * 32 * lda); rb0[i] = *(const u32x4*)(bg + (size_t)i * 32 * ldb); }
; #pragma unroll
;   for (int i = 0; i < 4; ++i) { ra1[i] = *(const u32x4*)(ag + (size_t)i * 32 * lda + 64); rb1[i] = *(const u32x4*)(bg + (size_t)i * 32 * ldb + 64); }
;   __syncthreads();
; #pragma unroll
;   for (int i = 0; i < 4; ++i) { *(u32x4*)(asw + 32 * i * 72) = ra0[i]; *(u32x4*)(bsw + 32 * i * 72) = rb0[i]; }
;   __syncthreads();
;   const int KT = K >> 6;
;   const u16* Asb = As + (wm * 64 + r) * 72 + hi * 8;
;   const u16* Bsb = Bs + (wn * 64 + r) * 72 + hi * 8;
;   auto compute = [&](int buf) __attribute__((always_inline)) {
;     bf16x8 af[2][2], bfr[2][2];
;     af[0][0] = *(const bf16x8*)(Asb + buf * 128 * 72);
;     af[0][1] = *(const bf16x8*)(Asb + buf * 128 * 72 + 32 * 72);
;     bfr[0][0] = *(const bf16x8*)(Bsb + buf * 128 * 72);
;     bfr[0][1] = *(const bf16x8*)(Bsb + buf * 128 * 72 + 32 * 72);
; #pragma unroll
;     for (int ks = 0; ks < 4; ++ks) {
;       const int c = ks & 1, n = c ^ 1;
;       if (ks < 3) {
;         af[n][0] = *(const bf16x8*)(Asb + buf * 128 * 72 + (ks + 1) * 16);
;         af[n][1] = *(const bf16x8*)(Asb + buf * 128 * 72 + 32 * 72 + (ks + 1) * 16);
;         bfr[n][0] = *(const bf16x8*)(Bsb + buf * 128 * 72 + (ks + 1) * 16);
;         bfr[n][1] = *(const bf16x8*)(Bsb + buf * 128 * 72 + 32 * 72 + (ks + 1) * 16);
;       }
;       __builtin_amdgcn_sched_barrier(0);
; #pragma unroll
;       for (int mi = 0; mi < 2; ++mi)
; #pragma unroll
;         for (int ni = 0; ni < 2; ++ni) {
;           if (SWAP) acc[mi][ni] = MFMA(bfr[c][ni], af[c][mi], acc[mi][ni]);
;           else acc[mi][ni] = MFMA(af[c][mi], bfr[c][ni], acc[mi][ni]);
;         }
;       __builtin_amdgcn_sched_barrier(0);
;     }
;   };
;   for (int kt = 0; kt < KT; kt += 2) {
.LBB0_746:
	s_ashr_i32 s8, s17, 31
	s_lshr_b32 s8, s8, 26
	s_add_i32 s8, s17, s8
	s_and_b32 s9, s8, 0x1ffffc0
	s_sub_i32 s9, s17, s9
	s_lshl_b32 s18, s9, 7
	s_lshl_b32 s8, s8, 1
	v_or_b32_e32 v2, s18, v1
	s_and_b32 s19, s8, 0xffffff80
	v_ashrrev_i32_e32 v3, 31, v2
	v_lshlrev_b64 v[22:23], 12, v[2:3]
	v_or_b32_e32 v2, s19, v1
	v_lshl_add_u64 v[4:5], v[132:133], 0, v[22:23]
	v_ashrrev_i32_e32 v3, 31, v2
	v_lshlrev_b64 v[24:25], 12, v[2:3]
	v_add_co_u32_e32 v8, vcc, s14, v4
	v_lshl_add_u64 v[6:7], v[134:135], 0, v[24:25]
	s_nop 0
	v_addc_co_u32_e32 v9, vcc, 0, v5, vcc
	v_add_co_u32_e32 v10, vcc, s14, v6
	global_load_dwordx4 v[66:69], v[4:5], off
	global_load_dwordx4 v[70:73], v[6:7], off
	v_addc_co_u32_e32 v11, vcc, 0, v7, vcc
	v_add_co_u32_e32 v12, vcc, s15, v4
	global_load_dwordx4 v[74:77], v[8:9], off
	global_load_dwordx4 v[78:81], v[10:11], off
	v_addc_co_u32_e32 v13, vcc, 0, v5, vcc
	v_add_co_u32_e32 v14, vcc, s15, v6
	global_load_dwordx4 v[82:85], v[12:13], off
	s_nop 0
	v_addc_co_u32_e32 v15, vcc, 0, v7, vcc
	v_add_co_u32_e32 v16, vcc, s16, v6
	global_load_dwordx4 v[86:89], v[14:15], off
	s_nop 0
	v_addc_co_u32_e32 v17, vcc, 0, v7, vcc
	v_add_co_u32_e32 v18, vcc, s16, v4
	global_load_dwordx4 v[94:97], v[16:17], off
	s_nop 0
	v_addc_co_u32_e32 v19, vcc, 0, v5, vcc
	global_load_dwordx4 v[90:93], v[18:19], off
	global_load_dwordx4 v[98:101], v[4:5], off offset:128
	global_load_dwordx4 v[102:105], v[6:7], off offset:128
	global_load_dwordx4 v[106:109], v[8:9], off offset:128
	global_load_dwordx4 v[110:113], v[10:11], off offset:128
	global_load_dwordx4 v[114:117], v[12:13], off offset:128
	global_load_dwordx4 v[118:121], v[14:15], off offset:128
	global_load_dwordx4 v[122:125], v[18:19], off offset:128
	global_load_dwordx4 v[126:129], v[16:17], off offset:128
	s_mov_b32 s20, 0
	v_mov_b32_e32 v2, 0
	v_mov_b32_e32 v3, v131
	v_mov_b32_e32 v4, v131
	v_mov_b32_e32 v5, v131
	v_mov_b32_e32 v6, v131
	v_mov_b32_e32 v7, v131
	v_mov_b32_e32 v8, v131
	v_mov_b32_e32 v9, v131
	v_mov_b32_e32 v10, v131
	v_mov_b32_e32 v11, v131
	v_mov_b32_e32 v12, v131
	v_mov_b32_e32 v13, v131
	v_mov_b32_e32 v14, v131
	v_mov_b32_e32 v15, v131
	v_mov_b32_e32 v16, v131
	v_mov_b32_e32 v17, v131
	v_mov_b32_e32 v18, 0
	v_mov_b32_e32 v19, v131
	v_mov_b32_e32 v20, v131
	v_lshl_add_u64 v[136:137], s[82:83], 0, v[24:25]
	v_lshl_add_u64 v[138:139], s[82:83], 0, v[22:23]
	v_mov_b32_e32 v21, v131
	v_mov_b32_e32 v22, v131
	v_mov_b32_e32 v23, v131
	v_mov_b32_e32 v24, v131
	v_mov_b32_e32 v25, v131
	v_mov_b32_e32 v26, v131
	v_mov_b32_e32 v27, v131
	v_mov_b32_e32 v28, v131
	v_mov_b32_e32 v29, v131
	v_mov_b32_e32 v30, v131
	v_mov_b32_e32 v31, v131
	v_mov_b32_e32 v32, v131
	v_mov_b32_e32 v33, v131
	v_mov_b32_e32 v34, 0
	v_mov_b32_e32 v35, v131
	v_mov_b32_e32 v36, v131
	v_mov_b32_e32 v37, v131
	v_mov_b32_e32 v38, v131
	v_mov_b32_e32 v39, v131
	v_mov_b32_e32 v40, v131
	v_mov_b32_e32 v41, v131
	v_mov_b32_e32 v42, v131
	v_mov_b32_e32 v43, v131
	v_mov_b32_e32 v44, v131
	v_mov_b32_e32 v45, v131
	v_mov_b32_e32 v46, v131
	v_mov_b32_e32 v47, v131
	v_mov_b32_e32 v48, v131
	v_mov_b32_e32 v49, v131
	v_mov_b32_e32 v50, 0
	v_mov_b32_e32 v51, v131
	v_mov_b32_e32 v52, v131
	v_mov_b32_e32 v53, v131
	v_mov_b32_e32 v54, v131
	v_mov_b32_e32 v55, v131
	v_mov_b32_e32 v56, v131
	v_mov_b32_e32 v57, v131
	v_mov_b32_e32 v58, v131
	v_mov_b32_e32 v59, v131
	v_mov_b32_e32 v60, v131
	v_mov_b32_e32 v61, v131
	v_mov_b32_e32 v62, v131
	v_mov_b32_e32 v63, v131
	v_mov_b32_e32 v64, v131
	v_mov_b32_e32 v65, v131
	s_waitcnt lgkmcnt(0)
	s_barrier
	s_waitcnt vmcnt(14)
	ds_write_b128 v144, v[70:73] offset:36880
	ds_write_b128 v144, v[66:69] offset:16
	s_waitcnt vmcnt(12)
	ds_write_b128 v144, v[78:81] offset:41488
	s_waitcnt vmcnt(10)
	ds_write_b128 v144, v[86:89] offset:46096
	s_waitcnt vmcnt(9)
	ds_write_b128 v144, v[94:97] offset:50704
	ds_write_b128 v144, v[74:77] offset:4624
	ds_write_b128 v144, v[82:85] offset:9232
	s_waitcnt vmcnt(8)
	ds_write_b128 v144, v[90:93] offset:13840
	s_waitcnt lgkmcnt(0)
	s_barrier
	s_branch .LBB0_748
.LBB0_748:
	v_lshl_add_u64 v[142:143], v[138:139], 0, v[130:131]
	v_lshl_add_u64 v[140:141], v[136:137], 0, v[130:131]
	v_add_co_u32_e32 v66, vcc, 0x10638000, v142
	s_nop 1
	v_addc_co_u32_e32 v67, vcc, 0, v143, vcc
	v_add_co_u32_e32 v70, vcc, 0x14b8000, v140
	global_load_dwordx4 v[66:69], v[66:67], off offset:256
	s_nop 0
	v_addc_co_u32_e32 v71, vcc, 0, v141, vcc
	v_add_co_u32_e32 v74, vcc, 0x10658000, v142
	global_load_dwordx4 v[70:73], v[70:71], off offset:256
	s_nop 0
	v_addc_co_u32_e32 v75, vcc, 0, v143, vcc
	v_add_co_u32_e32 v78, vcc, 0x14d8000, v140
	global_load_dwordx4 v[74:77], v[74:75], off offset:256
	s_nop 0
	v_addc_co_u32_e32 v79, vcc, 0, v141, vcc
	v_add_co_u32_e32 v82, vcc, 0x10678000, v142
	global_load_dwordx4 v[78:81], v[78:79], off offset:256
	s_nop 0
	v_addc_co_u32_e32 v83, vcc, 0, v143, vcc
	v_add_co_u32_e32 v86, vcc, 0x14f8000, v140
	global_load_dwordx4 v[82:85], v[82:83], off offset:256
	s_nop 0
	v_addc_co_u32_e32 v87, vcc, 0, v141, vcc
	v_add_co_u32_e32 v90, vcc, 0x10698000, v142
	global_load_dwordx4 v[86:89], v[86:87], off offset:256
	s_nop 0
	v_addc_co_u32_e32 v91, vcc, 0, v143, vcc
	v_add_co_u32_e32 v94, vcc, 0x1518000, v140
	global_load_dwordx4 v[90:93], v[90:91], off offset:256
	s_nop 0
	v_addc_co_u32_e32 v95, vcc, 0, v141, vcc
	global_load_dwordx4 v[94:97], v[94:95], off offset:256
	ds_read_b128 v[150:153], v147 offset:16
	ds_read_b128 v[154:157], v147 offset:48
	ds_read_b128 v[158:161], v147 offset:4624
	ds_read_b128 v[162:165], v147 offset:4656
	ds_read_b128 v[166:169], v148 offset:36880
	ds_read_b128 v[170:173], v148 offset:36912
	ds_read_b128 v[174:177], v148 offset:41488
	ds_read_b128 v[178:181], v148 offset:41520
	s_waitcnt lgkmcnt(3)
; #define MFMA(a, b, c) __builtin_amdgcn_mfma_f32_32x32x16_bf16((a), (b), (c), 0, 0, 0)
; template <bool SWAP, class Epi>
; DI void gemm_tile(const u16* __restrict__ A, int lda, const u16* __restrict__ Bt, int ldb, int K, int m0, int n0, char* smem, Epi&& epi) {
;     ...
;   auto compute = [&](int buf) __attribute__((always_inline)) {
;     bf16x8 af[2][2], bfr[2][2];
;     af[0][0] = *(const bf16x8*)(Asb + buf * 128 * 72);
;     af[0][1] = *(const bf16x8*)(Asb + buf * 128 * 72 + 32 * 72);
;     bfr[0][0] = *(const bf16x8*)(Bsb + buf * 128 * 72);
;     bfr[0][1] = *(const bf16x8*)(Bsb + buf * 128 * 72 + 32 * 72);
; #pragma unroll
;     for (int ks = 0; ks < 4; ++ks) {
;       const int c = ks & 1, n = c ^ 1;
;       if (ks < 3) {
;         af[n][0] = *(const bf16x8*)(Asb + buf * 128 * 72 + (ks + 1) * 16);
;         af[n][1] = *(const bf16x8*)(Asb + buf * 128 * 72 + 32 * 72 + (ks + 1) * 16);
;         bfr[n][0] = *(const bf16x8*)(Bsb + buf * 128 * 72 + (ks + 1) * 16);
;         bfr[n][1] = *(const bf16x8*)(Bsb + buf * 128 * 72 + 32 * 72 + (ks + 1) * 16);
;       }
;       __builtin_amdgcn_sched_barrier(0);
; #pragma unroll
;       for (int mi = 0; mi < 2; ++mi)
; #pragma unroll
;         for (int ni = 0; ni < 2; ++ni) {
;           if (SWAP) acc[mi][ni] = MFMA(bfr[c][ni], af[c][mi], acc[mi][ni]);
;           else acc[mi][ni] = MFMA(af[c][mi], bfr[c][ni], acc[mi][ni]);
;         }
;       __builtin_amdgcn_sched_barrier(0);
;     }
;   };
;   for (int kt = 0; kt < KT; kt += 2) {
;     if (kt + 2 < KT) {
;       const int k0 = (kt + 2) << 6;
; #pragma unroll
;       for (int i = 0; i < 4; ++i) { ra0[i] = *(const u32x4*)(ag + (size_t)i * 32 * lda + k0); rb0[i] = *(const u32x4*)(bg + (size_t)i * 32 * ldb + k0); }
;     }
;     compute(0);
; #pragma unroll
;     for (int i = 0; i < 4; ++i) { *(u32x4*)(asw + 128 * 72 + 32 * i * 72) = ra1[i]; *(u32x4*)(bsw + 128 * 72 + 32 * i * 72) = rb1[i]; }
;     __syncthreads();
;     if (kt + 3 < KT) {
;       const int k0 = (kt + 3) << 6;
; #pragma unroll
;       for (int i = 0; i < 4; ++i) { ra1[i] = *(const u32x4*)(ag + (size_t)i * 32 * lda + k0); rb1[i] = *(const u32x4*)(bg + (size_t)i * 32 * ldb + k0); }
;     }
;     compute(1);
;     if (kt + 2 < KT) {
; #pragma unroll
;       for (int i = 0; i < 4; ++i) { *(u32x4*)(asw + 32 * i * 72) = ra0[i]; *(u32x4*)(bsw + 32 * i * 72) = rb0[i]; }
;     }
;     __syncthreads();
	v_mfma_f32_32x32x16_bf16 v[50:65], v[166:169], v[150:153], v[50:65]
	s_waitcnt lgkmcnt(1)
	v_mfma_f32_32x32x16_bf16 v[34:49], v[174:177], v[150:153], v[34:49]
	v_mfma_f32_32x32x16_bf16 v[18:33], v[166:169], v[158:161], v[18:33]
	v_mfma_f32_32x32x16_bf16 v[2:17], v[174:177], v[158:161], v[2:17]
	ds_read_b128 v[150:153], v147 offset:80
	ds_read_b128 v[158:161], v147 offset:4688
	ds_read_b128 v[166:169], v148 offset:36944
	ds_read_b128 v[174:177], v148 offset:41552
	v_mfma_f32_32x32x16_bf16 v[50:65], v[170:173], v[154:157], v[50:65]
	s_waitcnt lgkmcnt(4)
	v_mfma_f32_32x32x16_bf16 v[34:49], v[178:181], v[154:157], v[34:49]
	v_mfma_f32_32x32x16_bf16 v[18:33], v[170:173], v[162:165], v[18:33]
	v_mfma_f32_32x32x16_bf16 v[2:17], v[178:181], v[162:165], v[2:17]
	ds_read_b128 v[154:157], v147 offset:112
	ds_read_b128 v[162:165], v147 offset:4720
	ds_read_b128 v[170:173], v148 offset:36976
	ds_read_b128 v[178:181], v148 offset:41584
	s_waitcnt lgkmcnt(5)
	v_mfma_f32_32x32x16_bf16 v[50:65], v[166:169], v[150:153], v[50:65]
	s_waitcnt vmcnt(14)
	ds_write_b128 v144, v[98:101] offset:18448
	ds_write_b128 v144, v[102:105] offset:55312
	s_waitcnt lgkmcnt(6)
	v_mfma_f32_32x32x16_bf16 v[34:49], v[174:177], v[150:153], v[34:49]
	v_mfma_f32_32x32x16_bf16 v[18:33], v[166:169], v[158:161], v[18:33]
	s_waitcnt vmcnt(12)
	ds_write_b128 v144, v[106:109] offset:23056
	ds_write_b128 v144, v[110:113] offset:59920
	v_mfma_f32_32x32x16_bf16 v[2:17], v[174:177], v[158:161], v[2:17]
	s_waitcnt vmcnt(10)
	ds_write_b128 v144, v[114:117] offset:27664
	ds_write_b128 v144, v[118:121] offset:64528
	s_waitcnt lgkmcnt(7)
	v_mfma_f32_32x32x16_bf16 v[50:65], v[170:173], v[154:157], v[50:65]
	s_waitcnt vmcnt(8)
	ds_write_b128 v144, v[122:125] offset:32272
	ds_write_b128 v145, v[126:129] offset:32256
	s_waitcnt lgkmcnt(8)
	v_mfma_f32_32x32x16_bf16 v[34:49], v[178:181], v[154:157], v[34:49]
	v_mfma_f32_32x32x16_bf16 v[18:33], v[170:173], v[162:165], v[18:33]
	v_mfma_f32_32x32x16_bf16 v[2:17], v[178:181], v[162:165], v[2:17]
	s_waitcnt lgkmcnt(0)
	s_barrier
	v_add_co_u32_e32 v98, vcc, 0x10638000, v142
	s_nop 1
	v_addc_co_u32_e32 v99, vcc, 0, v143, vcc
	v_add_co_u32_e32 v102, vcc, 0x14b8000, v140
	global_load_dwordx4 v[98:101], v[98:99], off offset:384
	s_nop 0
	v_addc_co_u32_e32 v103, vcc, 0, v141, vcc
	v_add_co_u32_e32 v106, vcc, 0x10658000, v142
	global_load_dwordx4 v[102:105], v[102:103], off offset:384
	s_nop 0
	v_addc_co_u32_e32 v107, vcc, 0, v143, vcc
	v_add_co_u32_e32 v110, vcc, 0x14d8000, v140
	global_load_dwordx4 v[106:109], v[106:107], off offset:384
	s_nop 0
	v_addc_co_u32_e32 v111, vcc, 0, v141, vcc
	v_add_co_u32_e32 v114, vcc, 0x10678000, v142
	global_load_dwordx4 v[110:113], v[110:111], off offset:384
	s_nop 0
	v_addc_co_u32_e32 v115, vcc, 0, v143, vcc
	v_add_co_u32_e32 v118, vcc, 0x14f8000, v140
	global_load_dwordx4 v[114:117], v[114:115], off offset:384
	s_nop 0
	v_addc_co_u32_e32 v119, vcc, 0, v141, vcc
	v_add_co_u32_e32 v122, vcc, 0x10698000, v142
	global_load_dwordx4 v[118:121], v[118:119], off offset:384
	s_nop 0
	v_addc_co_u32_e32 v123, vcc, 0, v143, vcc
	v_add_co_u32_e32 v126, vcc, 0x1518000, v140
	global_load_dwordx4 v[122:125], v[122:123], off offset:384
	s_nop 0
	v_addc_co_u32_e32 v127, vcc, 0, v141, vcc
	global_load_dwordx4 v[126:129], v[126:127], off offset:384
	ds_read_b128 v[140:143], v147 offset:18448
	ds_read_b128 v[150:153], v147 offset:18480
	ds_read_b128 v[154:157], v147 offset:23056
	ds_read_b128 v[158:161], v147 offset:23088
	ds_read_b128 v[162:165], v148 offset:55312
	ds_read_b128 v[166:169], v148 offset:55344
	ds_read_b128 v[170:173], v148 offset:59920
	ds_read_b128 v[174:177], v148 offset:59952
	s_waitcnt lgkmcnt(3)
	v_mfma_f32_32x32x16_bf16 v[50:65], v[162:165], v[140:143], v[50:65]
	s_waitcnt lgkmcnt(1)
	v_mfma_f32_32x32x16_bf16 v[34:49], v[170:173], v[140:143], v[34:49]
	v_mfma_f32_32x32x16_bf16 v[18:33], v[162:165], v[154:157], v[18:33]
	v_mfma_f32_32x32x16_bf16 v[2:17], v[170:173], v[154:157], v[2:17]
	ds_read_b128 v[140:143], v147 offset:18512
	ds_read_b128 v[154:157], v147 offset:23120
	ds_read_b128 v[162:165], v148 offset:55376
	ds_read_b128 v[170:173], v148 offset:59984
	v_mfma_f32_32x32x16_bf16 v[50:65], v[166:169], v[150:153], v[50:65]
	s_waitcnt lgkmcnt(4)
	v_mfma_f32_32x32x16_bf16 v[34:49], v[174:177], v[150:153], v[34:49]
	v_mfma_f32_32x32x16_bf16 v[18:33], v[166:169], v[158:161], v[18:33]
	v_mfma_f32_32x32x16_bf16 v[2:17], v[174:177], v[158:161], v[2:17]
	ds_read_b128 v[150:153], v147 offset:18544
	ds_read_b128 v[158:161], v147 offset:23152
	ds_read_b128 v[166:169], v148 offset:55408
	ds_read_b128 v[174:177], v148 offset:60016
	s_waitcnt lgkmcnt(5)
	v_mfma_f32_32x32x16_bf16 v[50:65], v[162:165], v[140:143], v[50:65]
	s_waitcnt vmcnt(14)
	ds_write_b128 v144, v[66:69] offset:16
	ds_write_b128 v144, v[70:73] offset:36880
	s_waitcnt lgkmcnt(6)
	v_mfma_f32_32x32x16_bf16 v[34:49], v[170:173], v[140:143], v[34:49]
	v_mfma_f32_32x32x16_bf16 v[18:33], v[162:165], v[154:157], v[18:33]
	s_waitcnt vmcnt(12)
	ds_write_b128 v144, v[74:77] offset:4624
	ds_write_b128 v144, v[78:81] offset:41488
	v_mfma_f32_32x32x16_bf16 v[2:17], v[170:173], v[154:157], v[2:17]
	s_waitcnt vmcnt(10)
	ds_write_b128 v144, v[82:85] offset:9232
	ds_write_b128 v144, v[86:89] offset:46096
	s_waitcnt lgkmcnt(7)
	v_mfma_f32_32x32x16_bf16 v[50:65], v[166:169], v[150:153], v[50:65]
	s_waitcnt vmcnt(8)
	ds_write_b128 v144, v[90:93] offset:13840
	ds_write_b128 v144, v[94:97] offset:50704
	s_waitcnt lgkmcnt(8)
	v_mfma_f32_32x32x16_bf16 v[34:49], v[174:177], v[150:153], v[34:49]
	v_mfma_f32_32x32x16_bf16 v[18:33], v[166:169], v[158:161], v[18:33]
	v_mfma_f32_32x32x16_bf16 v[2:17], v[174:177], v[158:161], v[2:17]
	s_add_i32 s20, s20, 2
	v_lshl_add_u64 v[136:137], v[136:137], 0, s[4:5]
	v_lshl_add_u64 v[138:139], v[138:139], 0, s[4:5]
	s_waitcnt lgkmcnt(0)
	s_barrier
; #define MFMA(a, b, c) __builtin_amdgcn_mfma_f32_32x32x16_bf16((a), (b), (c), 0, 0, 0)
; template <bool SWAP, class Epi>
; DI void gemm_tile(const u16* __restrict__ A, int lda, const u16* __restrict__ Bt, int ldb, int K, int m0, int n0, char* smem, Epi&& epi) {
;     ...
;   auto compute = [&](int buf) __attribute__((always_inline)) {
;     bf16x8 af[2][2], bfr[2][2];
;     af[0][0] = *(const bf16x8*)(Asb + buf * 128 * 72);
;     af[0][1] = *(const bf16x8*)(Asb + buf * 128 * 72 + 32 * 72);
;     bfr[0][0] = *(const bf16x8*)(Bsb + buf * 128 * 72);
;     bfr[0][1] = *(const bf16x8*)(Bsb + buf * 128 * 72 + 32 * 72);
; #pragma unroll
;     for (int ks = 0; ks < 4; ++ks) {
;       const int c = ks & 1, n = c ^ 1;
;       if (ks < 3) {
;         af[n][0] = *(const bf16x8*)(Asb + buf * 128 * 72 + (ks + 1) * 16);
;         af[n][1] = *(const bf16x8*)(Asb + buf * 128 * 72 + 32 * 72 + (ks + 1) * 16);
;         bfr[n][0] = *(const bf16x8*)(Bsb + buf * 128 * 72 + (ks + 1) * 16);
;         bfr[n][1] = *(const bf16x8*)(Bsb + buf * 128 * 72 + 32 * 72 + (ks + 1) * 16);
;       }
;       __builtin_amdgcn_sched_barrier(0);
; #pragma unroll
;       for (int mi = 0; mi < 2; ++mi)
; #pragma unroll
;         for (int ni = 0; ni < 2; ++ni) {
;           if (SWAP) acc[mi][ni] = MFMA(bfr[c][ni], af[c][mi], acc[mi][ni]);
;           else acc[mi][ni] = MFMA(af[c][mi], bfr[c][ni], acc[mi][ni]);
;         }
;       __builtin_amdgcn_sched_barrier(0);
;     }
;   };
;   for (int kt = 0; kt < KT; kt += 2) {
;     if (kt + 2 < KT) {
;       const int k0 = (kt + 2) << 6;
; #pragma unroll
;       for (int i = 0; i < 4; ++i) { ra0[i] = *(const u32x4*)(ag + (size_t)i * 32 * lda + k0); rb0[i] = *(const u32x4*)(bg + (size_t)i * 32 * ldb + k0); }
;     }
;     compute(0);
; #pragma unroll
;     for (int i = 0; i < 4; ++i) { *(u32x4*)(asw + 128 * 72 + 32 * i * 72) = ra1[i]; *(u32x4*)(bsw + 128 * 72 + 32 * i * 72) = rb1[i]; }
;     __syncthreads();
;     if (kt + 3 < KT) {
;       const int k0 = (kt + 3) << 6;
; #pragma unroll
;       for (int i = 0; i < 4; ++i) { ra1[i] = *(const u32x4*)(ag + (size_t)i * 32 * lda + k0); rb1[i] = *(const u32x4*)(bg + (size_t)i * 32 * ldb + k0); }
;     }
;     compute(1);
;     if (kt + 2 < KT) {
; #pragma unroll
;       for (int i = 0; i < 4; ++i) { *(u32x4*)(asw + 32 * i * 72) = ra0[i]; *(u32x4*)(bsw + 32 * i * 72) = rb0[i]; }
;     }
;     __syncthreads();
	s_cmp_lt_u32 s20, 30
	s_cbranch_scc1 .LBB0_748
	ds_read_b128 v[150:153], v147 offset:16
	ds_read_b128 v[154:157], v147 offset:48
	ds_read_b128 v[158:161], v147 offset:4624
	ds_read_b128 v[162:165], v147 offset:4656
	ds_read_b128 v[166:169], v148 offset:36880
	ds_read_b128 v[170:173], v148 offset:36912
	ds_read_b128 v[174:177], v148 offset:41488
	ds_read_b128 v[178:181], v148 offset:41520
	s_waitcnt lgkmcnt(3)
	v_mfma_f32_32x32x16_bf16 v[50:65], v[166:169], v[150:153], v[50:65]
	s_waitcnt lgkmcnt(1)
	v_mfma_f32_32x32x16_bf16 v[34:49], v[174:177], v[150:153], v[34:49]
	v_mfma_f32_32x32x16_bf16 v[18:33], v[166:169], v[158:161], v[18:33]
	v_mfma_f32_32x32x16_bf16 v[2:17], v[174:177], v[158:161], v[2:17]
	ds_read_b128 v[150:153], v147 offset:80
	ds_read_b128 v[158:161], v147 offset:4688
	ds_read_b128 v[166:169], v148 offset:36944
	ds_read_b128 v[174:177], v148 offset:41552
	v_mfma_f32_32x32x16_bf16 v[50:65], v[170:173], v[154:157], v[50:65]
	s_waitcnt lgkmcnt(4)
	v_mfma_f32_32x32x16_bf16 v[34:49], v[178:181], v[154:157], v[34:49]
	v_mfma_f32_32x32x16_bf16 v[18:33], v[170:173], v[162:165], v[18:33]
	v_mfma_f32_32x32x16_bf16 v[2:17], v[178:181], v[162:165], v[2:17]
	ds_read_b128 v[154:157], v147 offset:112
	ds_read_b128 v[162:165], v147 offset:4720
	ds_read_b128 v[170:173], v148 offset:36976
	ds_read_b128 v[178:181], v148 offset:41584
	s_waitcnt lgkmcnt(5)
	v_mfma_f32_32x32x16_bf16 v[50:65], v[166:169], v[150:153], v[50:65]
	s_waitcnt vmcnt(6)
	ds_write_b128 v144, v[98:101] offset:18448
	ds_write_b128 v144, v[102:105] offset:55312
	s_waitcnt lgkmcnt(6)
	v_mfma_f32_32x32x16_bf16 v[34:49], v[174:177], v[150:153], v[34:49]
	v_mfma_f32_32x32x16_bf16 v[18:33], v[166:169], v[158:161], v[18:33]
	s_waitcnt vmcnt(4)
	ds_write_b128 v144, v[106:109] offset:23056
	ds_write_b128 v144, v[110:113] offset:59920
	v_mfma_f32_32x32x16_bf16 v[2:17], v[174:177], v[158:161], v[2:17]
	s_waitcnt vmcnt(2)
	ds_write_b128 v144, v[114:117] offset:27664
	ds_write_b128 v144, v[118:121] offset:64528
	s_waitcnt lgkmcnt(7)
	v_mfma_f32_32x32x16_bf16 v[50:65], v[170:173], v[154:157], v[50:65]
	s_waitcnt vmcnt(0)
	ds_write_b128 v144, v[122:125] offset:32272
	ds_write_b128 v145, v[126:129] offset:32256
	s_waitcnt lgkmcnt(8)
	v_mfma_f32_32x32x16_bf16 v[34:49], v[178:181], v[154:157], v[34:49]
	v_mfma_f32_32x32x16_bf16 v[18:33], v[170:173], v[162:165], v[18:33]
	v_mfma_f32_32x32x16_bf16 v[2:17], v[178:181], v[162:165], v[2:17]
	s_waitcnt lgkmcnt(0)
	s_barrier
	ds_read_b128 v[140:143], v147 offset:18448
	ds_read_b128 v[150:153], v147 offset:18480
	ds_read_b128 v[154:157], v147 offset:23056
	ds_read_b128 v[158:161], v147 offset:23088
	ds_read_b128 v[162:165], v148 offset:55312
	ds_read_b128 v[166:169], v148 offset:55344
	ds_read_b128 v[170:173], v148 offset:59920
	ds_read_b128 v[174:177], v148 offset:59952
	s_waitcnt lgkmcnt(3)
	v_mfma_f32_32x32x16_bf16 v[50:65], v[162:165], v[140:143], v[50:65]
	s_waitcnt lgkmcnt(1)
	v_mfma_f32_32x32x16_bf16 v[34:49], v[170:173], v[140:143], v[34:49]
	v_mfma_f32_32x32x16_bf16 v[18:33], v[162:165], v[154:157], v[18:33]
	v_mfma_f32_32x32x16_bf16 v[2:17], v[170:173], v[154:157], v[2:17]
	ds_read_b128 v[140:143], v147 offset:18512
	ds_read_b128 v[154:157], v147 offset:23120
	ds_read_b128 v[162:165], v148 offset:55376
	ds_read_b128 v[170:173], v148 offset:59984
	v_mfma_f32_32x32x16_bf16 v[50:65], v[166:169], v[150:153], v[50:65]
	s_waitcnt lgkmcnt(4)
	v_mfma_f32_32x32x16_bf16 v[34:49], v[174:177], v[150:153], v[34:49]
	v_mfma_f32_32x32x16_bf16 v[18:33], v[166:169], v[158:161], v[18:33]
	v_mfma_f32_32x32x16_bf16 v[2:17], v[174:177], v[158:161], v[2:17]
	ds_read_b128 v[150:153], v147 offset:18544
	ds_read_b128 v[158:161], v147 offset:23152
	ds_read_b128 v[166:169], v148 offset:55408
	ds_read_b128 v[174:177], v148 offset:60016
	s_waitcnt lgkmcnt(5)
	v_mfma_f32_32x32x16_bf16 v[50:65], v[162:165], v[140:143], v[50:65]
	s_waitcnt lgkmcnt(4)
	v_mfma_f32_32x32x16_bf16 v[34:49], v[170:173], v[140:143], v[34:49]
	v_mfma_f32_32x32x16_bf16 v[18:33], v[162:165], v[154:157], v[18:33]
	v_mfma_f32_32x32x16_bf16 v[2:17], v[170:173], v[154:157], v[2:17]
	s_waitcnt lgkmcnt(1)
	v_mfma_f32_32x32x16_bf16 v[50:65], v[166:169], v[150:153], v[50:65]
	s_waitcnt lgkmcnt(0)
	v_mfma_f32_32x32x16_bf16 v[34:49], v[174:177], v[150:153], v[34:49]
	v_mfma_f32_32x32x16_bf16 v[18:33], v[166:169], v[158:161], v[18:33]
	v_mfma_f32_32x32x16_bf16 v[2:17], v[174:177], v[158:161], v[2:17]
	s_waitcnt lgkmcnt(0)
	s_barrier
	s_branch .LBB0_745

; template <bool SWAP, class Epi>
; DI void gemm_tile(const u16* __restrict__ A, int lda, const u16* __restrict__ Bt, int ldb, int K, int m0, int n0, char* smem, Epi&& epi) {
;     ...
;       for (int i = 0; i < 16; ++i) acc[a][b][i] = 0.f;
;   const int srow = tid >> 3, skc = tid & 7;
;   const u16* ag = A + (size_t)(m0 + srow) * lda + skc * 8;
;   const u16* bg = Bt + (size_t)(n0 + srow) * ldb + skc * 8;
;   u16* asw = As + srow * 72 + skc * 8;
;   u16* bsw = Bs + srow * 72 + skc * 8;
;   u32x4 ra0[4], rb0[4], ra1[4], rb1[4];
; #pragma unroll
;   for (int i = 0; i < 4; ++i) { ra0[i] = *(const u32x4*)(ag + (size_t)i * 32 * lda); rb0[i] = *(const u32x4*)(bg + (size_t)i * 32 * ldb); }
; #pragma unroll
;   for (int i = 0; i < 4; ++i) { ra1[i] = *(const u32x4*)(ag + (size_t)i * 32 * lda + 64); rb1[i] = *(const u32x4*)(bg + (size_t)i * 32 * ldb + 64); }
;   __syncthreads();
; #pragma unroll
;   for (int i = 0; i < 4; ++i) { *(u32x4*)(asw + 32 * i * 72) = ra0[i]; *(u32x4*)(bsw + 32 * i * 72) = rb0[i]; }
;   __syncthreads();
;   const int KT = K >> 6;
;   const u16* Asb = As + (wm * 64 + r) * 72 + hi * 8;
;   const u16* Bsb = Bs + (wn * 64 + r) * 72 + hi * 8;
;   auto compute = [&](int buf) __attribute__((always_inline)) {
;     bf16x8 af[2][2], bfr[2][2];
;     af[0][0] = *(const bf16x8*)(Asb + buf * 128 * 72);
;     af[0][1] = *(const bf16x8*)(Asb + buf * 128 * 72 + 32 * 72);
;     bfr[0][0] = *(const bf16x8*)(Bsb + buf * 128 * 72);
;     bfr[0][1] = *(const bf16x8*)(Bsb + buf * 128 * 72 + 32 * 72);
; #pragma unroll
;     for (int ks = 0; ks < 4; ++ks) {
;       const int c = ks & 1, n = c ^ 1;
;       if (ks < 3) {
;         af[n][0] = *(const bf16x8*)(Asb + buf * 128 * 72 + (ks + 1) * 16);
;         af[n][1] = *(const bf16x8*)(Asb + buf * 128 * 72 + 32 * 72 + (ks + 1) * 16);
;         bfr[n][0] = *(const bf16x8*)(Bsb + buf * 128 * 72 + (ks + 1) * 16);
;         bfr[n][1] = *(const bf16x8*)(Bsb + buf * 128 * 72 + 32 * 72 + (ks + 1) * 16);
;       }
;       __builtin_amdgcn_sched_barrier(0);
; #pragma unroll
;       for (int mi = 0; mi < 2; ++mi)
; #pragma unroll
;         for (int ni = 0; ni < 2; ++ni) {
;           if (SWAP) acc[mi][ni] = MFMA(bfr[c][ni], af[c][mi], acc[mi][ni]);
;           else acc[mi][ni] = MFMA(af[c][mi], bfr[c][ni], acc[mi][ni]);
;         }
;       __builtin_amdgcn_sched_barrier(0);
;     }
;   };
;   for (int kt = 0; kt < KT; kt += 2) {
.LBB0_953:
	s_ashr_i32 s6, s15, 31
	s_lshr_b32 s6, s6, 26
	s_add_i32 s6, s15, s6
	s_and_b32 s7, s6, 0x1ffffc0
	s_sub_i32 s7, s15, s7
	s_lshl_b32 s16, s7, 7
	s_lshl_b32 s6, s6, 1
	v_or_b32_e32 v2, s16, v1
	s_and_b32 s17, s6, 0xffffff80
	v_ashrrev_i32_e32 v3, 31, v2
	v_lshlrev_b64 v[22:23], 12, v[2:3]
	v_or_b32_e32 v2, s17, v1
	v_lshl_add_u64 v[4:5], v[132:133], 0, v[22:23]
	v_ashrrev_i32_e32 v3, 31, v2
	v_lshlrev_b64 v[24:25], 12, v[2:3]
	v_add_co_u32_e32 v8, vcc, s11, v4
	v_lshl_add_u64 v[6:7], v[134:135], 0, v[24:25]
	s_nop 0
	v_addc_co_u32_e32 v9, vcc, 0, v5, vcc
	v_add_co_u32_e32 v10, vcc, s11, v6
	global_load_dwordx4 v[66:69], v[4:5], off
	global_load_dwordx4 v[70:73], v[6:7], off
	v_addc_co_u32_e32 v11, vcc, 0, v7, vcc
	v_add_co_u32_e32 v12, vcc, s13, v4
	global_load_dwordx4 v[74:77], v[8:9], off
	global_load_dwordx4 v[78:81], v[10:11], off
	v_addc_co_u32_e32 v13, vcc, 0, v5, vcc
	v_add_co_u32_e32 v14, vcc, s13, v6
	global_load_dwordx4 v[82:85], v[12:13], off
	s_nop 0
	v_addc_co_u32_e32 v15, vcc, 0, v7, vcc
	v_add_co_u32_e32 v16, vcc, s14, v6
	global_load_dwordx4 v[86:89], v[14:15], off
	s_nop 0
	v_addc_co_u32_e32 v17, vcc, 0, v7, vcc
	v_add_co_u32_e32 v18, vcc, s14, v4
	global_load_dwordx4 v[94:97], v[16:17], off
	s_nop 0
	v_addc_co_u32_e32 v19, vcc, 0, v5, vcc
	global_load_dwordx4 v[90:93], v[18:19], off
	global_load_dwordx4 v[98:101], v[4:5], off offset:128
	global_load_dwordx4 v[102:105], v[6:7], off offset:128
	global_load_dwordx4 v[106:109], v[8:9], off offset:128
	global_load_dwordx4 v[110:113], v[10:11], off offset:128
	global_load_dwordx4 v[114:117], v[12:13], off offset:128
	global_load_dwordx4 v[118:121], v[14:15], off offset:128
	global_load_dwordx4 v[122:125], v[18:19], off offset:128
	global_load_dwordx4 v[126:129], v[16:17], off offset:128
	s_mov_b32 s18, 0
	v_mov_b32_e32 v2, 0
	v_mov_b32_e32 v3, v131
	v_mov_b32_e32 v4, v131
	v_mov_b32_e32 v5, v131
	v_mov_b32_e32 v6, v131
	v_mov_b32_e32 v7, v131
	v_mov_b32_e32 v8, v131
	v_mov_b32_e32 v9, v131
	v_mov_b32_e32 v10, v131
	v_mov_b32_e32 v11, v131
	v_mov_b32_e32 v12, v131
	v_mov_b32_e32 v13, v131
	v_mov_b32_e32 v14, v131
	v_mov_b32_e32 v15, v131
	v_mov_b32_e32 v16, v131
	v_mov_b32_e32 v17, v131
	v_mov_b32_e32 v18, 0
	v_mov_b32_e32 v19, v131
	v_mov_b32_e32 v20, v131
	v_lshl_add_u64 v[136:137], s[82:83], 0, v[24:25]
	v_lshl_add_u64 v[138:139], s[82:83], 0, v[22:23]
	v_mov_b32_e32 v21, v131
	v_mov_b32_e32 v22, v131
	v_mov_b32_e32 v23, v131
	v_mov_b32_e32 v24, v131
	v_mov_b32_e32 v25, v131
	v_mov_b32_e32 v26, v131
	v_mov_b32_e32 v27, v131
	v_mov_b32_e32 v28, v131
	v_mov_b32_e32 v29, v131
	v_mov_b32_e32 v30, v131
	v_mov_b32_e32 v31, v131
	v_mov_b32_e32 v32, v131
	v_mov_b32_e32 v33, v131
	v_mov_b32_e32 v34, 0
	v_mov_b32_e32 v35, v131
	v_mov_b32_e32 v36, v131
	v_mov_b32_e32 v37, v131
	v_mov_b32_e32 v38, v131
	v_mov_b32_e32 v39, v131
	v_mov_b32_e32 v40, v131
	v_mov_b32_e32 v41, v131
	v_mov_b32_e32 v42, v131
	v_mov_b32_e32 v43, v131
	v_mov_b32_e32 v44, v131
	v_mov_b32_e32 v45, v131
	v_mov_b32_e32 v46, v131
	v_mov_b32_e32 v47, v131
	v_mov_b32_e32 v48, v131
	v_mov_b32_e32 v49, v131
	v_mov_b32_e32 v50, 0
	v_mov_b32_e32 v51, v131
	v_mov_b32_e32 v52, v131
	v_mov_b32_e32 v53, v131
	v_mov_b32_e32 v54, v131
	v_mov_b32_e32 v55, v131
	v_mov_b32_e32 v56, v131
	v_mov_b32_e32 v57, v131
	v_mov_b32_e32 v58, v131
	v_mov_b32_e32 v59, v131
	v_mov_b32_e32 v60, v131
	v_mov_b32_e32 v61, v131
	v_mov_b32_e32 v62, v131
	v_mov_b32_e32 v63, v131
	v_mov_b32_e32 v64, v131
	v_mov_b32_e32 v65, v131
	s_waitcnt lgkmcnt(0)
	s_barrier
	s_waitcnt vmcnt(14)
	ds_write_b128 v144, v[70:73] offset:36880
	ds_write_b128 v144, v[66:69] offset:16
	s_waitcnt vmcnt(12)
	ds_write_b128 v144, v[78:81] offset:41488
	s_waitcnt vmcnt(10)
	ds_write_b128 v144, v[86:89] offset:46096
	s_waitcnt vmcnt(9)
	ds_write_b128 v144, v[94:97] offset:50704
	ds_write_b128 v144, v[74:77] offset:4624
	ds_write_b128 v144, v[82:85] offset:9232
	s_waitcnt vmcnt(8)
	ds_write_b128 v144, v[90:93] offset:13840
	s_waitcnt lgkmcnt(0)
	s_barrier
	s_branch .LBB0_955
.LBB0_955:
	v_lshl_add_u64 v[142:143], v[138:139], 0, v[130:131]
	v_lshl_add_u64 v[140:141], v[136:137], 0, v[130:131]
	v_add_co_u32_e32 v66, vcc, 0x6538000, v142
	s_nop 1
	v_addc_co_u32_e32 v67, vcc, 0, v143, vcc
	v_add_co_u32_e32 v70, vcc, 0x1cb8000, v140
	global_load_dwordx4 v[66:69], v[66:67], off offset:256
	s_nop 0
	v_addc_co_u32_e32 v71, vcc, 0, v141, vcc
	v_add_co_u32_e32 v74, vcc, 0x6558000, v142
	global_load_dwordx4 v[70:73], v[70:71], off offset:256
	s_nop 0
	v_addc_co_u32_e32 v75, vcc, 0, v143, vcc
	v_add_co_u32_e32 v78, vcc, 0x1cd8000, v140
	global_load_dwordx4 v[74:77], v[74:75], off offset:256
	s_nop 0
	v_addc_co_u32_e32 v79, vcc, 0, v141, vcc
	v_add_co_u32_e32 v82, vcc, 0x6578000, v142
	global_load_dwordx4 v[78:81], v[78:79], off offset:256
	s_nop 0
	v_addc_co_u32_e32 v83, vcc, 0, v143, vcc
	v_add_co_u32_e32 v86, vcc, 0x1cf8000, v140
	global_load_dwordx4 v[82:85], v[82:83], off offset:256
	s_nop 0
	v_addc_co_u32_e32 v87, vcc, 0, v141, vcc
	v_add_co_u32_e32 v90, vcc, 0x6598000, v142
	global_load_dwordx4 v[86:89], v[86:87], off offset:256
	s_nop 0
	v_addc_co_u32_e32 v91, vcc, 0, v143, vcc
	v_add_co_u32_e32 v94, vcc, 0x1d18000, v140
	global_load_dwordx4 v[90:93], v[90:91], off offset:256
	s_nop 0
	v_addc_co_u32_e32 v95, vcc, 0, v141, vcc
	global_load_dwordx4 v[94:97], v[94:95], off offset:256
	ds_read_b128 v[150:153], v147 offset:16
	ds_read_b128 v[154:157], v147 offset:48
	ds_read_b128 v[158:161], v147 offset:4624
	ds_read_b128 v[162:165], v147 offset:4656
	ds_read_b128 v[166:169], v148 offset:36880
	ds_read_b128 v[170:173], v148 offset:36912
	ds_read_b128 v[174:177], v148 offset:41488
	ds_read_b128 v[178:181], v148 offset:41520
	s_waitcnt lgkmcnt(3)
; #define MFMA(a, b, c) __builtin_amdgcn_mfma_f32_32x32x16_bf16((a), (b), (c), 0, 0, 0)
; template <bool SWAP, class Epi>
; DI void gemm_tile(const u16* __restrict__ A, int lda, const u16* __restrict__ Bt, int ldb, int K, int m0, int n0, char* smem, Epi&& epi) {
;     ...
;   auto compute = [&](int buf) __attribute__((always_inline)) {
;     bf16x8 af[2][2], bfr[2][2];
;     af[0][0] = *(const bf16x8*)(Asb + buf * 128 * 72);
;     af[0][1] = *(const bf16x8*)(Asb + buf * 128 * 72 + 32 * 72);
;     bfr[0][0] = *(const bf16x8*)(Bsb + buf * 128 * 72);
;     bfr[0][1] = *(const bf16x8*)(Bsb + buf * 128 * 72 + 32 * 72);
; #pragma unroll
;     for (int ks = 0; ks < 4; ++ks) {
;       const int c = ks & 1, n = c ^ 1;
;       if (ks < 3) {
;         af[n][0] = *(const bf16x8*)(Asb + buf * 128 * 72 + (ks + 1) * 16);
;         af[n][1] = *(const bf16x8*)(Asb + buf * 128 * 72 + 32 * 72 + (ks + 1) * 16);
;         bfr[n][0] = *(const bf16x8*)(Bsb + buf * 128 * 72 + (ks + 1) * 16);
;         bfr[n][1] = *(const bf16x8*)(Bsb + buf * 128 * 72 + 32 * 72 + (ks + 1) * 16);
;       }
;       __builtin_amdgcn_sched_barrier(0);
; #pragma unroll
;       for (int mi = 0; mi < 2; ++mi)
; #pragma unroll
;         for (int ni = 0; ni < 2; ++ni) {
;           if (SWAP) acc[mi][ni] = MFMA(bfr[c][ni], af[c][mi], acc[mi][ni]);
;           else acc[mi][ni] = MFMA(af[c][mi], bfr[c][ni], acc[mi][ni]);
;         }
;       __builtin_amdgcn_sched_barrier(0);
;     }
;   };
;   for (int kt = 0; kt < KT; kt += 2) {
;     if (kt + 2 < KT) {
;       const int k0 = (kt + 2) << 6;
; #pragma unroll
;       for (int i = 0; i < 4; ++i) { ra0[i] = *(const u32x4*)(ag + (size_t)i * 32 * lda + k0); rb0[i] = *(const u32x4*)(bg + (size_t)i * 32 * ldb + k0); }
;     }
;     compute(0);
; #pragma unroll
;     for (int i = 0; i < 4; ++i) { *(u32x4*)(asw + 128 * 72 + 32 * i * 72) = ra1[i]; *(u32x4*)(bsw + 128 * 72 + 32 * i * 72) = rb1[i]; }
;     __syncthreads();
;     if (kt + 3 < KT) {
;       const int k0 = (kt + 3) << 6;
; #pragma unroll
;       for (int i = 0; i < 4; ++i) { ra1[i] = *(const u32x4*)(ag + (size_t)i * 32 * lda + k0); rb1[i] = *(const u32x4*)(bg + (size_t)i * 32 * ldb + k0); }
;     }
;     compute(1);
;     if (kt + 2 < KT) {
; #pragma unroll
;       for (int i = 0; i < 4; ++i) { *(u32x4*)(asw + 32 * i * 72) = ra0[i]; *(u32x4*)(bsw + 32 * i * 72) = rb0[i]; }
;     }
;     __syncthreads();
	v_mfma_f32_32x32x16_bf16 v[50:65], v[166:169], v[150:153], v[50:65]
	s_waitcnt lgkmcnt(1)
	v_mfma_f32_32x32x16_bf16 v[34:49], v[174:177], v[150:153], v[34:49]
	v_mfma_f32_32x32x16_bf16 v[18:33], v[166:169], v[158:161], v[18:33]
	v_mfma_f32_32x32x16_bf16 v[2:17], v[174:177], v[158:161], v[2:17]
	ds_read_b128 v[150:153], v147 offset:80
	ds_read_b128 v[158:161], v147 offset:4688
	ds_read_b128 v[166:169], v148 offset:36944
	ds_read_b128 v[174:177], v148 offset:41552
	v_mfma_f32_32x32x16_bf16 v[50:65], v[170:173], v[154:157], v[50:65]
	s_waitcnt lgkmcnt(4)
	v_mfma_f32_32x32x16_bf16 v[34:49], v[178:181], v[154:157], v[34:49]
	v_mfma_f32_32x32x16_bf16 v[18:33], v[170:173], v[162:165], v[18:33]
	v_mfma_f32_32x32x16_bf16 v[2:17], v[178:181], v[162:165], v[2:17]
	ds_read_b128 v[154:157], v147 offset:112
	ds_read_b128 v[162:165], v147 offset:4720
	ds_read_b128 v[170:173], v148 offset:36976
	ds_read_b128 v[178:181], v148 offset:41584
	s_waitcnt lgkmcnt(5)
	v_mfma_f32_32x32x16_bf16 v[50:65], v[166:169], v[150:153], v[50:65]
	s_waitcnt vmcnt(14)
	ds_write_b128 v144, v[98:101] offset:18448
	ds_write_b128 v144, v[102:105] offset:55312
	s_waitcnt lgkmcnt(6)
	v_mfma_f32_32x32x16_bf16 v[34:49], v[174:177], v[150:153], v[34:49]
	v_mfma_f32_32x32x16_bf16 v[18:33], v[166:169], v[158:161], v[18:33]
	s_waitcnt vmcnt(12)
	ds_write_b128 v144, v[106:109] offset:23056
	ds_write_b128 v144, v[110:113] offset:59920
	v_mfma_f32_32x32x16_bf16 v[2:17], v[174:177], v[158:161], v[2:17]
	s_waitcnt vmcnt(10)
	ds_write_b128 v144, v[114:117] offset:27664
	ds_write_b128 v144, v[118:121] offset:64528
	s_waitcnt lgkmcnt(7)
	v_mfma_f32_32x32x16_bf16 v[50:65], v[170:173], v[154:157], v[50:65]
	s_waitcnt vmcnt(8)
	ds_write_b128 v144, v[122:125] offset:32272
	ds_write_b128 v145, v[126:129] offset:32256
	s_waitcnt lgkmcnt(8)
	v_mfma_f32_32x32x16_bf16 v[34:49], v[178:181], v[154:157], v[34:49]
	v_mfma_f32_32x32x16_bf16 v[18:33], v[170:173], v[162:165], v[18:33]
	v_mfma_f32_32x32x16_bf16 v[2:17], v[178:181], v[162:165], v[2:17]
	s_waitcnt lgkmcnt(0)
	s_barrier
	v_add_co_u32_e32 v98, vcc, 0x6538000, v142
	s_nop 1
	v_addc_co_u32_e32 v99, vcc, 0, v143, vcc
	v_add_co_u32_e32 v102, vcc, 0x1cb8000, v140
	global_load_dwordx4 v[98:101], v[98:99], off offset:384
	s_nop 0
	v_addc_co_u32_e32 v103, vcc, 0, v141, vcc
	v_add_co_u32_e32 v106, vcc, 0x6558000, v142
	global_load_dwordx4 v[102:105], v[102:103], off offset:384
	s_nop 0
	v_addc_co_u32_e32 v107, vcc, 0, v143, vcc
	v_add_co_u32_e32 v110, vcc, 0x1cd8000, v140
	global_load_dwordx4 v[106:109], v[106:107], off offset:384
	s_nop 0
	v_addc_co_u32_e32 v111, vcc, 0, v141, vcc
	v_add_co_u32_e32 v114, vcc, 0x6578000, v142
	global_load_dwordx4 v[110:113], v[110:111], off offset:384
	s_nop 0
	v_addc_co_u32_e32 v115, vcc, 0, v143, vcc
	v_add_co_u32_e32 v118, vcc, 0x1cf8000, v140
	global_load_dwordx4 v[114:117], v[114:115], off offset:384
	s_nop 0
	v_addc_co_u32_e32 v119, vcc, 0, v141, vcc
	v_add_co_u32_e32 v122, vcc, 0x6598000, v142
	global_load_dwordx4 v[118:121], v[118:119], off offset:384
	s_nop 0
	v_addc_co_u32_e32 v123, vcc, 0, v143, vcc
	v_add_co_u32_e32 v126, vcc, 0x1d18000, v140
	global_load_dwordx4 v[122:125], v[122:123], off offset:384
	s_nop 0
	v_addc_co_u32_e32 v127, vcc, 0, v141, vcc
	global_load_dwordx4 v[126:129], v[126:127], off offset:384
	ds_read_b128 v[140:143], v147 offset:18448
	ds_read_b128 v[150:153], v147 offset:18480
	ds_read_b128 v[154:157], v147 offset:23056
	ds_read_b128 v[158:161], v147 offset:23088
	ds_read_b128 v[162:165], v148 offset:55312
	ds_read_b128 v[166:169], v148 offset:55344
	ds_read_b128 v[170:173], v148 offset:59920
	ds_read_b128 v[174:177], v148 offset:59952
	s_waitcnt lgkmcnt(3)
	v_mfma_f32_32x32x16_bf16 v[50:65], v[162:165], v[140:143], v[50:65]
	s_waitcnt lgkmcnt(1)
	v_mfma_f32_32x32x16_bf16 v[34:49], v[170:173], v[140:143], v[34:49]
	v_mfma_f32_32x32x16_bf16 v[18:33], v[162:165], v[154:157], v[18:33]
	v_mfma_f32_32x32x16_bf16 v[2:17], v[170:173], v[154:157], v[2:17]
	ds_read_b128 v[140:143], v147 offset:18512
	ds_read_b128 v[154:157], v147 offset:23120
	ds_read_b128 v[162:165], v148 offset:55376
	ds_read_b128 v[170:173], v148 offset:59984
	v_mfma_f32_32x32x16_bf16 v[50:65], v[166:169], v[150:153], v[50:65]
	s_waitcnt lgkmcnt(4)
	v_mfma_f32_32x32x16_bf16 v[34:49], v[174:177], v[150:153], v[34:49]
	v_mfma_f32_32x32x16_bf16 v[18:33], v[166:169], v[158:161], v[18:33]
	v_mfma_f32_32x32x16_bf16 v[2:17], v[174:177], v[158:161], v[2:17]
	ds_read_b128 v[150:153], v147 offset:18544
	ds_read_b128 v[158:161], v147 offset:23152
	ds_read_b128 v[166:169], v148 offset:55408
	ds_read_b128 v[174:177], v148 offset:60016
	s_waitcnt lgkmcnt(5)
	v_mfma_f32_32x32x16_bf16 v[50:65], v[162:165], v[140:143], v[50:65]
	s_waitcnt vmcnt(14)
	ds_write_b128 v144, v[66:69] offset:16
	ds_write_b128 v144, v[70:73] offset:36880
	s_waitcnt lgkmcnt(6)
	v_mfma_f32_32x32x16_bf16 v[34:49], v[170:173], v[140:143], v[34:49]
	v_mfma_f32_32x32x16_bf16 v[18:33], v[162:165], v[154:157], v[18:33]
	s_waitcnt vmcnt(12)
	ds_write_b128 v144, v[74:77] offset:4624
	ds_write_b128 v144, v[78:81] offset:41488
	v_mfma_f32_32x32x16_bf16 v[2:17], v[170:173], v[154:157], v[2:17]
	s_waitcnt vmcnt(10)
	ds_write_b128 v144, v[82:85] offset:9232
	ds_write_b128 v144, v[86:89] offset:46096
	s_waitcnt lgkmcnt(7)
	v_mfma_f32_32x32x16_bf16 v[50:65], v[166:169], v[150:153], v[50:65]
	s_waitcnt vmcnt(8)
	ds_write_b128 v144, v[90:93] offset:13840
	ds_write_b128 v144, v[94:97] offset:50704
	s_waitcnt lgkmcnt(8)
	v_mfma_f32_32x32x16_bf16 v[34:49], v[174:177], v[150:153], v[34:49]
	v_mfma_f32_32x32x16_bf16 v[18:33], v[166:169], v[158:161], v[18:33]
	v_mfma_f32_32x32x16_bf16 v[2:17], v[174:177], v[158:161], v[2:17]
	s_add_i32 s18, s18, 2
	v_lshl_add_u64 v[136:137], v[136:137], 0, s[4:5]
	v_lshl_add_u64 v[138:139], v[138:139], 0, s[4:5]
	s_waitcnt lgkmcnt(0)
	s_barrier
; #define MFMA(a, b, c) __builtin_amdgcn_mfma_f32_32x32x16_bf16((a), (b), (c), 0, 0, 0)
; template <bool SWAP, class Epi>
; DI void gemm_tile(const u16* __restrict__ A, int lda, const u16* __restrict__ Bt, int ldb, int K, int m0, int n0, char* smem, Epi&& epi) {
;     ...
;   auto compute = [&](int buf) __attribute__((always_inline)) {
;     bf16x8 af[2][2], bfr[2][2];
;     af[0][0] = *(const bf16x8*)(Asb + buf * 128 * 72);
;     af[0][1] = *(const bf16x8*)(Asb + buf * 128 * 72 + 32 * 72);
;     bfr[0][0] = *(const bf16x8*)(Bsb + buf * 128 * 72);
;     bfr[0][1] = *(const bf16x8*)(Bsb + buf * 128 * 72 + 32 * 72);
; #pragma unroll
;     for (int ks = 0; ks < 4; ++ks) {
;       const int c = ks & 1, n = c ^ 1;
;       if (ks < 3) {
;         af[n][0] = *(const bf16x8*)(Asb + buf * 128 * 72 + (ks + 1) * 16);
;         af[n][1] = *(const bf16x8*)(Asb + buf * 128 * 72 + 32 * 72 + (ks + 1) * 16);
;         bfr[n][0] = *(const bf16x8*)(Bsb + buf * 128 * 72 + (ks + 1) * 16);
;         bfr[n][1] = *(const bf16x8*)(Bsb + buf * 128 * 72 + 32 * 72 + (ks + 1) * 16);
;       }
;       __builtin_amdgcn_sched_barrier(0);
; #pragma unroll
;       for (int mi = 0; mi < 2; ++mi)
; #pragma unroll
;         for (int ni = 0; ni < 2; ++ni) {
;           if (SWAP) acc[mi][ni] = MFMA(bfr[c][ni], af[c][mi], acc[mi][ni]);
;           else acc[mi][ni] = MFMA(af[c][mi], bfr[c][ni], acc[mi][ni]);
;         }
;       __builtin_amdgcn_sched_barrier(0);
;     }
;   };
;   for (int kt = 0; kt < KT; kt += 2) {
;     if (kt + 2 < KT) {
;       const int k0 = (kt + 2) << 6;
; #pragma unroll
;       for (int i = 0; i < 4; ++i) { ra0[i] = *(const u32x4*)(ag + (size_t)i * 32 * lda + k0); rb0[i] = *(const u32x4*)(bg + (size_t)i * 32 * ldb + k0); }
;     }
;     compute(0);
; #pragma unroll
;     for (int i = 0; i < 4; ++i) { *(u32x4*)(asw + 128 * 72 + 32 * i * 72) = ra1[i]; *(u32x4*)(bsw + 128 * 72 + 32 * i * 72) = rb1[i]; }
;     __syncthreads();
;     if (kt + 3 < KT) {
;       const int k0 = (kt + 3) << 6;
; #pragma unroll
;       for (int i = 0; i < 4; ++i) { ra1[i] = *(const u32x4*)(ag + (size_t)i * 32 * lda + k0); rb1[i] = *(const u32x4*)(bg + (size_t)i * 32 * ldb + k0); }
;     }
;     compute(1);
;     if (kt + 2 < KT) {
; #pragma unroll
;       for (int i = 0; i < 4; ++i) { *(u32x4*)(asw + 32 * i * 72) = ra0[i]; *(u32x4*)(bsw + 32 * i * 72) = rb0[i]; }
;     }
;     __syncthreads();
	s_cmp_lt_u32 s18, 30
	s_cbranch_scc1 .LBB0_955
	ds_read_b128 v[150:153], v147 offset:16
	ds_read_b128 v[154:157], v147 offset:48
	ds_read_b128 v[158:161], v147 offset:4624
	ds_read_b128 v[162:165], v147 offset:4656
	ds_read_b128 v[166:169], v148 offset:36880
	ds_read_b128 v[170:173], v148 offset:36912
	ds_read_b128 v[174:177], v148 offset:41488
	ds_read_b128 v[178:181], v148 offset:41520
	s_waitcnt lgkmcnt(3)
	v_mfma_f32_32x32x16_bf16 v[50:65], v[166:169], v[150:153], v[50:65]
	s_waitcnt lgkmcnt(1)
	v_mfma_f32_32x32x16_bf16 v[34:49], v[174:177], v[150:153], v[34:49]
	v_mfma_f32_32x32x16_bf16 v[18:33], v[166:169], v[158:161], v[18:33]
	v_mfma_f32_32x32x16_bf16 v[2:17], v[174:177], v[158:161], v[2:17]
	ds_read_b128 v[150:153], v147 offset:80
	ds_read_b128 v[158:161], v147 offset:4688
	ds_read_b128 v[166:169], v148 offset:36944
	ds_read_b128 v[174:177], v148 offset:41552
	v_mfma_f32_32x32x16_bf16 v[50:65], v[170:173], v[154:157], v[50:65]
	s_waitcnt lgkmcnt(4)
	v_mfma_f32_32x32x16_bf16 v[34:49], v[178:181], v[154:157], v[34:49]
	v_mfma_f32_32x32x16_bf16 v[18:33], v[170:173], v[162:165], v[18:33]
	v_mfma_f32_32x32x16_bf16 v[2:17], v[178:181], v[162:165], v[2:17]
	ds_read_b128 v[154:157], v147 offset:112
	ds_read_b128 v[162:165], v147 offset:4720
	ds_read_b128 v[170:173], v148 offset:36976
	ds_read_b128 v[178:181], v148 offset:41584
	s_waitcnt lgkmcnt(5)
	v_mfma_f32_32x32x16_bf16 v[50:65], v[166:169], v[150:153], v[50:65]
	s_waitcnt vmcnt(6)
	ds_write_b128 v144, v[98:101] offset:18448
	ds_write_b128 v144, v[102:105] offset:55312
	s_waitcnt lgkmcnt(6)
	v_mfma_f32_32x32x16_bf16 v[34:49], v[174:177], v[150:153], v[34:49]
	v_mfma_f32_32x32x16_bf16 v[18:33], v[166:169], v[158:161], v[18:33]
	s_waitcnt vmcnt(4)
	ds_write_b128 v144, v[106:109] offset:23056
	ds_write_b128 v144, v[110:113] offset:59920
	v_mfma_f32_32x32x16_bf16 v[2:17], v[174:177], v[158:161], v[2:17]
	s_waitcnt vmcnt(2)
	ds_write_b128 v144, v[114:117] offset:27664
	ds_write_b128 v144, v[118:121] offset:64528
	s_waitcnt lgkmcnt(7)
	v_mfma_f32_32x32x16_bf16 v[50:65], v[170:173], v[154:157], v[50:65]
	s_waitcnt vmcnt(0)
	ds_write_b128 v144, v[122:125] offset:32272
	ds_write_b128 v145, v[126:129] offset:32256
	s_waitcnt lgkmcnt(8)
	v_mfma_f32_32x32x16_bf16 v[34:49], v[178:181], v[154:157], v[34:49]
	v_mfma_f32_32x32x16_bf16 v[18:33], v[170:173], v[162:165], v[18:33]
	v_mfma_f32_32x32x16_bf16 v[2:17], v[178:181], v[162:165], v[2:17]
	s_waitcnt lgkmcnt(0)
	s_barrier
	ds_read_b128 v[140:143], v147 offset:18448
	ds_read_b128 v[150:153], v147 offset:18480
	ds_read_b128 v[154:157], v147 offset:23056
	ds_read_b128 v[158:161], v147 offset:23088
	ds_read_b128 v[162:165], v148 offset:55312
	ds_read_b128 v[166:169], v148 offset:55344
	ds_read_b128 v[170:173], v148 offset:59920
	ds_read_b128 v[174:177], v148 offset:59952
	s_waitcnt lgkmcnt(3)
	v_mfma_f32_32x32x16_bf16 v[50:65], v[162:165], v[140:143], v[50:65]
	s_waitcnt lgkmcnt(1)
	v_mfma_f32_32x32x16_bf16 v[34:49], v[170:173], v[140:143], v[34:49]
	v_mfma_f32_32x32x16_bf16 v[18:33], v[162:165], v[154:157], v[18:33]
	v_mfma_f32_32x32x16_bf16 v[2:17], v[170:173], v[154:157], v[2:17]
	ds_read_b128 v[140:143], v147 offset:18512
	ds_read_b128 v[154:157], v147 offset:23120
	ds_read_b128 v[162:165], v148 offset:55376
	ds_read_b128 v[170:173], v148 offset:59984
	v_mfma_f32_32x32x16_bf16 v[50:65], v[166:169], v[150:153], v[50:65]
	s_waitcnt lgkmcnt(4)
	v_mfma_f32_32x32x16_bf16 v[34:49], v[174:177], v[150:153], v[34:49]
	v_mfma_f32_32x32x16_bf16 v[18:33], v[166:169], v[158:161], v[18:33]
	v_mfma_f32_32x32x16_bf16 v[2:17], v[174:177], v[158:161], v[2:17]
	ds_read_b128 v[150:153], v147 offset:18544
	ds_read_b128 v[158:161], v147 offset:23152
	ds_read_b128 v[166:169], v148 offset:55408
	ds_read_b128 v[174:177], v148 offset:60016
	s_waitcnt lgkmcnt(5)
	v_mfma_f32_32x32x16_bf16 v[50:65], v[162:165], v[140:143], v[50:65]
	s_waitcnt lgkmcnt(4)
	v_mfma_f32_32x32x16_bf16 v[34:49], v[170:173], v[140:143], v[34:49]
	v_mfma_f32_32x32x16_bf16 v[18:33], v[162:165], v[154:157], v[18:33]
	v_mfma_f32_32x32x16_bf16 v[2:17], v[170:173], v[154:157], v[2:17]
	s_waitcnt lgkmcnt(1)
	v_mfma_f32_32x32x16_bf16 v[50:65], v[166:169], v[150:153], v[50:65]
	s_waitcnt lgkmcnt(0)
	v_mfma_f32_32x32x16_bf16 v[34:49], v[174:177], v[150:153], v[34:49]
	v_mfma_f32_32x32x16_bf16 v[18:33], v[166:169], v[158:161], v[18:33]
	v_mfma_f32_32x32x16_bf16 v[2:17], v[174:177], v[158:161], v[2:17]
	s_waitcnt lgkmcnt(0)
	s_barrier
	s_branch .LBB0_952
